# GEMM main loops: per-phase s_setprio flips replaced by one static priority raise for waves 4-7 per GEMM phase
# baseline (speedup 1.0000x reference)
; #define PG8_STAGE(bufoff, gbase, voff) do { _Pragma("unroll") for (int _i = 0; _i < 2; ++_i) \
;         __builtin_amdgcn_global_load_lds((const unsigned*)((const char*)(gbase) + (voff)[_i]), (PG8_LAS unsigned*)(lds + (bufoff) + ldsw + _i * 8192), 16, 0, 0); } while (0)
; #define PG8_WAIT_V(n) asm volatile("s_waitcnt vmcnt(" #n ")" ::: "memory")
; #define PG8_BAR __builtin_amdgcn_s_barrier()
; template <class Epi, class Sched, bool ALIGN_EPI = false, bool SP2 = false>
; __device__ __forceinline__ void gemm_phase(PG8_LAS unsigned char* lds, const Gemm g, const Sched& S, const Epi& E) {
;     ...
;     const int tid = tid_, wid = __builtin_amdgcn_readfirstlane(tid >> 6), lane = tid & 63, wr = wid >> 2, wc = wid & 3, fr = lane & 15, fq = lane >> 4;
;     const int K = g.K, nt = K / BK;
;     unsigned voffA[2], voffB[2];
; #pragma unroll
;     for (int i = 0; i < 2; ++i) { int R, C; stage_rc(tid * 16 + i * 8192, R, C); const int Rb = Epi::PERM ? ((R & ~31) + perm32(R & 31)) : R;
;         voffA[i] = (unsigned)(R * K + C) * 2u; voffB[i] = (unsigned)(Rb * K + C) * 2u; }
;     const size_t kstep = (size_t)(BK * 2);
;     const size_t hstep = (size_t)HALF * K * 2;
;     const size_t tstep = 2 * hstep;
;     const unsigned ldsw = (unsigned)wid * 1024u;
;     const int aoff = lds_byte(wr * 64 + fr, fq * 8), boff = lds_byte(wc * 32 + fr, fq * 8);
;     ...
;         PG8_STAGE(PG8_SB(1, 0), cB + kstep, voffB); PG8_STAGE(PG8_SA(1, 0), cA + kstep, voffA); PG8_STAGE(PG8_SB(1, 1), cB + hstep + kstep, voffB);
;         PG8_WAIT_V(6); PG8_BAR;
.LBB0_134:
	s_add_u32 s12, s4, 0x6a00000
	s_addc_u32 s13, s5, 0
	s_lshl_b32 s14, s14, 5
	s_and_b32 s38, s14, 0x60
	s_add_i32 m0, s33, 0x18000
	v_lshl_add_u64 v[8:9], v[8:9], 0, s[96:97]
	s_lshl_b32 s16, s7, 13
	s_lshl_b32 s17, s38, 7
	s_waitcnt vmcnt(2)
	s_barrier
	global_load_lds_dwordx4 v[8:9], off
	v_lshl_add_u64 v[6:7], v[6:7], 0, s[96:97]
	s_add_i32 m0, s33, 0x1a000
	s_add_i32 s39, s33, 0x8000
	s_add_i32 s40, s33, 0xa000
	global_load_lds_dwordx4 v[6:7], off
	v_lshl_add_u64 v[2:3], v[2:3], 0, s[96:97]
	s_mov_b32 m0, s39
	s_add_u32 s14, s0, 0x40080
	global_load_lds_dwordx4 v[2:3], off
	v_lshl_add_u64 v[2:3], v[4:5], 0, s[96:97]
	s_mov_b32 m0, s40
	s_addc_u32 s15, s1, 0
	global_load_lds_dwordx4 v[2:3], off
	s_add_i32 m0, s33, 0x1c000
	v_lshl_add_u64 v[2:3], s[14:15], 0, v[134:135]
	global_load_lds_dwordx4 v[2:3], off
	v_lshl_add_u64 v[2:3], s[14:15], 0, v[130:131]
	s_add_i32 m0, s33, 0x1e000
	s_cmpk_lt_u32 s6, 0x100
	global_load_lds_dwordx4 v[2:3], off
	v_bfe_u32 v2, v0, 4, 2
	v_and_b32_e32 v3, 15, v0
	v_lshlrev_b32_e32 v138, 3, v2
	v_lshlrev_b32_e32 v2, 4, v2
	v_lshlrev_b32_e32 v0, 2, v0
	v_lshl_or_b32 v139, s7, 6, v3
	v_lshl_or_b32 v3, v3, 6, v2
	v_and_b32_e32 v0, 32, v0
	v_bitop3_b32 v6, v3, s16, v0 bitop3:0xde
	v_bitop3_b32 v163, v3, s17, v0 bitop3:0xde
	v_or_b32_e32 v0, s38, v138
	v_cmp_gt_u32_e64 s[6:7], s72, v0
	v_lshlrev_b32_e32 v0, 2, v0
	v_lshl_add_u64 v[4:5], s[4:5], 0, v[0:1]
	v_mov_b32_e32 v3, v1
	v_lshlrev_b32_e32 v0, 14, v10
	v_lshl_add_u64 v[2:3], s[4:5], 0, v[2:3]
	s_mov_b64 s[4:5], 0x1b800000
	v_and_b32_e32 v0, 0xffff8000, v0
	v_lshl_add_u64 v[142:143], v[2:3], 0, s[4:5]
	v_lshl_add_u32 v0, v11, 11, v0
	v_and_b32_e32 v2, 1, v10
	v_lshl_or_b32 v0, v2, 6, v0
	v_lshl_add_u32 v144, v12, 1, v0
	v_lshlrev_b32_e32 v0, 14, v14
	v_and_b32_e32 v0, 0xffff8000, v0
	s_waitcnt vmcnt(6)
	v_lshl_add_u32 v0, v13, 11, v0
	v_and_b32_e32 v2, 1, v14
	s_mov_b64 s[16:17], 0x16e00000
	v_lshl_or_b32 v0, v2, 6, v0
	v_readlane_b32 s4, v254, 7
	s_cselect_b64 s[14:15], -1, 0
	s_waitcnt lgkmcnt(0)
	s_ashr_i32 s41, s37, 31
	v_lshl_add_u64 v[140:141], v[4:5], 0, s[16:17]
	v_mov_b32_e32 v145, v1
	v_lshl_add_u32 v146, v15, 1, v0
	v_mov_b32_e32 v147, v1
	s_mov_b32 s42, 0
	v_add_u32_e32 v166, 0, v6
	v_readlane_b32 s43, v253, 62
	s_mov_b32 s44, s4
	s_barrier
	v_readlane_b32 s5, v254, 8
	v_readfirstlane_b32 s100, v210
	s_nop 3
	s_lshr_b32 s100, s100, 6
	s_cmp_lt_u32 s100, 4
	s_cbranch_scc1 .Lgp_g1
	s_setprio 1
.Lgp_g1:
	s_branch .LBB0_137

; #define PG8_STAGE(bufoff, gbase, voff) do { _Pragma("unroll") for (int _i = 0; _i < 2; ++_i) \
;         __builtin_amdgcn_global_load_lds((const unsigned*)((const char*)(gbase) + (voff)[_i]), (PG8_LAS unsigned*)(lds + (bufoff) + ldsw + _i * 8192), 16, 0, 0); } while (0)
; #define PG8_LDA(dst, b, h) do { _Pragma("unroll") for (int m = 0; m < 4; ++m) _Pragma("unroll") for (int k = 0; k < 2; ++k) dst[m][k] = *(const PG8_LAS bf16x8*)(lds + PG8_SA(b, h) + aoff + m * 2048 + k * 1024); } while (0)
; #define PG8_LDB(dst, b, h) do { _Pragma("unroll") for (int n = 0; n < 2; ++n) _Pragma("unroll") for (int k = 0; k < 2; ++k) dst[n][k] = *(const PG8_LAS bf16x8*)(lds + PG8_SB(b, h) + boff + n * 2048 + k * 1024); } while (0)
; #define PG8_MMA(ai, bj, At, Bt) do { __builtin_amdgcn_s_setprio(1); _Pragma("unroll") for (int m = 0; m < 4; ++m) _Pragma("unroll") for (int n = 0; n < 2; ++n) _Pragma("unroll") for (int k = 0; k < 2; ++k) \
;         acc[ai][bj][m][n] = __builtin_amdgcn_mfma_f32_16x16x32_bf16(Bt[n][k], At[m][k], acc[ai][bj][m][n], 0, 0, 0); __builtin_amdgcn_s_setprio(0); } while (0)
; #define PG8_WAIT_V(n) asm volatile("s_waitcnt vmcnt(" #n ")" ::: "memory")
; #define PG8_WAIT_L(n) asm volatile("s_waitcnt lgkmcnt(" #n ")" ::: "memory")
; #define PG8_BAR __builtin_amdgcn_s_barrier()
; #define PG8_SCHED __builtin_amdgcn_sched_barrier(0)
; template <class Epi, class Sched, bool ALIGN_EPI = false, bool SP2 = false>
; __device__ __forceinline__ void gemm_phase(PG8_LAS unsigned char* lds, const Gemm g, const Sched& S, const Epi& E) {
;     ...
;             PG8_LDB(B0, 0, 0); PG8_LDB(B1, 0, 1); PG8_SCHED; PG8_LDA(At, 0, 0); PG8_STAGE(PG8_SA(1, 1), a1 + hstep, voffA);
;             PG8_WAIT_V(8); PG8_WAIT_L(0); PG8_BAR; PG8_MMA(0, 0, At, B0); PG8_MMA(0, 1, At, B1); PG8_BAR; PG8_SCHED;
;             PG8_LDA(At, 0, 1); PG8_STAGE(PG8_SB(0, 0), b2, voffB); PG8_STAGE(PG8_SB(0, 1), b2 + hstep, voffB); PG8_STAGE(PG8_SA(0, 0), a2, voffA);
;             PG8_WAIT_V(8); PG8_WAIT_L(0); PG8_BAR; PG8_MMA(1, 0, At, B0); PG8_MMA(1, 1, At, B1); PG8_BAR; PG8_SCHED;
.LBB0_140:
	s_add_u32 s8, s0, 0xfffc0080
	s_addc_u32 s9, s1, -1
	s_add_i32 s50, 0, 0x10000
	s_cmp_eq_u32 s49, 12
	s_cselect_b32 s27, s19, s9
	s_cselect_b32 s26, s45, s8
	v_add_u32_e32 v0, s50, v163
	s_cselect_b32 s9, s17, s48
	s_cselect_b32 s8, s46, s47
	s_add_i32 s52, 0, 0x14000
	ds_read_b128 v[148:151], v0
	ds_read_b128 v[152:155], v0 offset:1024
	ds_read_b128 v[156:159], v0 offset:2048
	ds_read_b128 v[168:171], v0 offset:3072
	v_add_u32_e32 v0, s52, v163
	ds_read_b128 v[172:175], v0
	ds_read_b128 v[176:179], v0 offset:1024
	ds_read_b128 v[180:183], v0 offset:2048
	ds_read_b128 v[184:187], v0 offset:3072
	v_lshl_add_u64 v[160:161], s[0:1], 0, v[146:147]
	s_add_i32 m0, s33, 0xc000
	ds_read_b128 v[188:191], v166
	ds_read_b128 v[206:209], v166 offset:1024
	ds_read_b128 v[222:225], v166 offset:2048
	ds_read_b128 v[226:229], v166 offset:3072
	ds_read_b128 v[230:233], v166 offset:4096
	ds_read_b128 v[234:237], v166 offset:5120
	ds_read_b128 v[238:241], v166 offset:6144
	ds_read_b128 v[242:245], v166 offset:7168
	global_load_lds_dwordx4 v[160:161], off
	v_lshl_add_u64 v[160:161], s[0:1], 0, v[144:145]
	s_add_i32 m0, s33, 0xe000
	s_nop 0
	global_load_lds_dwordx4 v[160:161], off
	s_waitcnt vmcnt(8)
	s_waitcnt lgkmcnt(0)
	s_barrier
	s_nop 0
	s_waitcnt lgkmcnt(0)
	v_mfma_f32_16x16x32_bf16 v[126:129], v[148:151], v[188:191], v[126:129]
	v_mfma_f32_16x16x32_bf16 v[122:125], v[156:159], v[188:191], v[122:125]
	v_mfma_f32_16x16x32_bf16 v[110:113], v[148:151], v[222:225], v[110:113]
	v_mfma_f32_16x16x32_bf16 v[106:109], v[156:159], v[222:225], v[106:109]
	v_mfma_f32_16x16x32_bf16 v[94:97], v[148:151], v[230:233], v[94:97]
	v_mfma_f32_16x16x32_bf16 v[90:93], v[156:159], v[230:233], v[90:93]
	v_mfma_f32_16x16x32_bf16 v[78:81], v[148:151], v[238:241], v[78:81]
	v_mfma_f32_16x16x32_bf16 v[74:77], v[156:159], v[238:241], v[74:77]
	v_mfma_f32_16x16x32_bf16 v[126:129], v[152:155], v[206:209], v[126:129]
	v_mfma_f32_16x16x32_bf16 v[122:125], v[168:171], v[206:209], v[122:125]
	v_mfma_f32_16x16x32_bf16 v[110:113], v[152:155], v[226:229], v[110:113]
	v_mfma_f32_16x16x32_bf16 v[106:109], v[168:171], v[226:229], v[106:109]
	v_mfma_f32_16x16x32_bf16 v[94:97], v[152:155], v[234:237], v[94:97]
	v_mfma_f32_16x16x32_bf16 v[90:93], v[168:171], v[234:237], v[90:93]
	v_mfma_f32_16x16x32_bf16 v[78:81], v[152:155], v[242:245], v[78:81]
	v_mfma_f32_16x16x32_bf16 v[74:77], v[168:171], v[242:245], v[74:77]
	s_nop 0
	s_nop 0
	v_mfma_f32_16x16x32_bf16 v[118:121], v[172:175], v[188:191], v[118:121]
	v_mfma_f32_16x16x32_bf16 v[114:117], v[180:183], v[188:191], v[114:117]
	v_mfma_f32_16x16x32_bf16 v[102:105], v[172:175], v[222:225], v[102:105]
	v_mfma_f32_16x16x32_bf16 v[98:101], v[180:183], v[222:225], v[98:101]
	v_mfma_f32_16x16x32_bf16 v[86:89], v[172:175], v[230:233], v[86:89]
	v_mfma_f32_16x16x32_bf16 v[82:85], v[180:183], v[230:233], v[82:85]
	v_mfma_f32_16x16x32_bf16 v[70:73], v[172:175], v[238:241], v[70:73]
	v_mfma_f32_16x16x32_bf16 v[66:69], v[180:183], v[238:241], v[66:69]
	v_mfma_f32_16x16x32_bf16 v[118:121], v[176:179], v[206:209], v[118:121]
	v_mfma_f32_16x16x32_bf16 v[114:117], v[184:187], v[206:209], v[114:117]
	v_mfma_f32_16x16x32_bf16 v[102:105], v[176:179], v[226:229], v[102:105]
	v_mfma_f32_16x16x32_bf16 v[98:101], v[184:187], v[226:229], v[98:101]
	v_mfma_f32_16x16x32_bf16 v[86:89], v[176:179], v[234:237], v[86:89]
	v_mfma_f32_16x16x32_bf16 v[82:85], v[184:187], v[234:237], v[82:85]
	v_mfma_f32_16x16x32_bf16 v[70:73], v[176:179], v[242:245], v[70:73]
	v_mfma_f32_16x16x32_bf16 v[66:69], v[184:187], v[242:245], v[66:69]
	s_nop 0
	s_barrier
	s_add_i32 s50, s50, s31
	v_lshl_add_u64 v[160:161], s[8:9], 0, v[134:135]
	s_mov_b32 m0, s50
	ds_read_b128 v[188:191], v166 offset:16384
	ds_read_b128 v[206:209], v166 offset:17408
	ds_read_b128 v[222:225], v166 offset:18432
	ds_read_b128 v[226:229], v166 offset:19456
	ds_read_b128 v[230:233], v166 offset:20480
	ds_read_b128 v[234:237], v166 offset:21504
	ds_read_b128 v[238:241], v166 offset:22528
	ds_read_b128 v[242:245], v166 offset:23552
	global_load_lds_dwordx4 v[160:161], off
	s_add_i32 m0, s50, 0x2000
	s_add_u32 s50, s8, 0x40000
	v_lshl_add_u64 v[164:165], s[8:9], 0, v[130:131]
	s_addc_u32 s51, s9, 0
	s_add_i32 s52, s52, s31
	global_load_lds_dwordx4 v[164:165], off
	v_lshl_add_u64 v[192:193], s[50:51], 0, v[134:135]
	s_mov_b32 m0, s52
	v_lshl_add_u64 v[246:247], s[26:27], 0, v[132:133]
	global_load_lds_dwordx4 v[192:193], off
	v_lshl_add_u64 v[192:193], s[50:51], 0, v[130:131]
	s_add_i32 m0, s52, 0x2000
	s_nop 0
	global_load_lds_dwordx4 v[192:193], off
	v_lshl_add_u64 v[192:193], s[26:27], 0, v[136:137]
	s_mov_b32 m0, s33
	s_nop 0
	global_load_lds_dwordx4 v[192:193], off
	s_mov_b32 m0, s34
	s_nop 0
	global_load_lds_dwordx4 v[246:247], off
	s_waitcnt vmcnt(8)
	s_waitcnt lgkmcnt(0)
	s_barrier
; #define PG8_STAGE(bufoff, gbase, voff) do { _Pragma("unroll") for (int _i = 0; _i < 2; ++_i) \
;         __builtin_amdgcn_global_load_lds((const unsigned*)((const char*)(gbase) + (voff)[_i]), (PG8_LAS unsigned*)(lds + (bufoff) + ldsw + _i * 8192), 16, 0, 0); } while (0)
; #define PG8_LDA(dst, b, h) do { _Pragma("unroll") for (int m = 0; m < 4; ++m) _Pragma("unroll") for (int k = 0; k < 2; ++k) dst[m][k] = *(const PG8_LAS bf16x8*)(lds + PG8_SA(b, h) + aoff + m * 2048 + k * 1024); } while (0)
; #define PG8_LDB(dst, b, h) do { _Pragma("unroll") for (int n = 0; n < 2; ++n) _Pragma("unroll") for (int k = 0; k < 2; ++k) dst[n][k] = *(const PG8_LAS bf16x8*)(lds + PG8_SB(b, h) + boff + n * 2048 + k * 1024); } while (0)
; #define PG8_MMA(ai, bj, At, Bt) do { __builtin_amdgcn_s_setprio(1); _Pragma("unroll") for (int m = 0; m < 4; ++m) _Pragma("unroll") for (int n = 0; n < 2; ++n) _Pragma("unroll") for (int k = 0; k < 2; ++k) \
;         acc[ai][bj][m][n] = __builtin_amdgcn_mfma_f32_16x16x32_bf16(Bt[n][k], At[m][k], acc[ai][bj][m][n], 0, 0, 0); __builtin_amdgcn_s_setprio(0); } while (0)
; #define PG8_WAIT_V(n) asm volatile("s_waitcnt vmcnt(" #n ")" ::: "memory")
; #define PG8_WAIT_L(n) asm volatile("s_waitcnt lgkmcnt(" #n ")" ::: "memory")
; #define PG8_BAR __builtin_amdgcn_s_barrier()
; #define PG8_SCHED __builtin_amdgcn_sched_barrier(0)
; template <class Epi, class Sched, bool ALIGN_EPI = false, bool SP2 = false>
; __device__ __forceinline__ void gemm_phase(PG8_LAS unsigned char* lds, const Gemm g, const Sched& S, const Epi& E) {
;     ...
;             PG8_WAIT_V(8); PG8_WAIT_L(0); PG8_BAR; PG8_MMA(1, 0, At, B0); PG8_MMA(1, 1, At, B1); PG8_BAR; PG8_SCHED;
;             PG8_LDB(B0, 1, 0); PG8_LDB(B1, 1, 1); PG8_SCHED; PG8_LDA(At, 1, 0); PG8_STAGE(PG8_SA(0, 1), a2 + hstep, voffA);
;             PG8_WAIT_V(8); PG8_WAIT_L(0); PG8_BAR; PG8_MMA(0, 0, At, B0); PG8_MMA(0, 1, At, B1); PG8_BAR; PG8_SCHED;
	s_nop 0
	s_waitcnt lgkmcnt(0)
	v_mfma_f32_16x16x32_bf16 v[62:65], v[148:151], v[188:191], v[62:65]
	v_mfma_f32_16x16x32_bf16 v[58:61], v[156:159], v[188:191], v[58:61]
	v_mfma_f32_16x16x32_bf16 v[46:49], v[148:151], v[222:225], v[46:49]
	v_mfma_f32_16x16x32_bf16 v[42:45], v[156:159], v[222:225], v[42:45]
	v_mfma_f32_16x16x32_bf16 v[30:33], v[148:151], v[230:233], v[30:33]
	v_mfma_f32_16x16x32_bf16 v[26:29], v[156:159], v[230:233], v[26:29]
	v_mfma_f32_16x16x32_bf16 v[14:17], v[148:151], v[238:241], v[14:17]
	v_mfma_f32_16x16x32_bf16 v[10:13], v[156:159], v[238:241], v[10:13]
	v_mfma_f32_16x16x32_bf16 v[62:65], v[152:155], v[206:209], v[62:65]
	v_mfma_f32_16x16x32_bf16 v[58:61], v[168:171], v[206:209], v[58:61]
	v_mfma_f32_16x16x32_bf16 v[46:49], v[152:155], v[226:229], v[46:49]
	v_mfma_f32_16x16x32_bf16 v[42:45], v[168:171], v[226:229], v[42:45]
	v_mfma_f32_16x16x32_bf16 v[30:33], v[152:155], v[234:237], v[30:33]
	v_mfma_f32_16x16x32_bf16 v[26:29], v[168:171], v[234:237], v[26:29]
	v_mfma_f32_16x16x32_bf16 v[14:17], v[152:155], v[242:245], v[14:17]
	v_mfma_f32_16x16x32_bf16 v[10:13], v[168:171], v[242:245], v[10:13]
	s_nop 0
	s_nop 0
	v_mfma_f32_16x16x32_bf16 v[54:57], v[172:175], v[188:191], v[54:57]
	v_mfma_f32_16x16x32_bf16 v[50:53], v[180:183], v[188:191], v[50:53]
	v_mfma_f32_16x16x32_bf16 v[38:41], v[172:175], v[222:225], v[38:41]
	v_mfma_f32_16x16x32_bf16 v[34:37], v[180:183], v[222:225], v[34:37]
	v_mfma_f32_16x16x32_bf16 v[22:25], v[172:175], v[230:233], v[22:25]
	v_mfma_f32_16x16x32_bf16 v[18:21], v[180:183], v[230:233], v[18:21]
	v_mfma_f32_16x16x32_bf16 v[6:9], v[172:175], v[238:241], v[6:9]
	v_mfma_f32_16x16x32_bf16 v[2:5], v[180:183], v[238:241], v[2:5]
	v_mfma_f32_16x16x32_bf16 v[54:57], v[176:179], v[206:209], v[54:57]
	v_mfma_f32_16x16x32_bf16 v[50:53], v[184:187], v[206:209], v[50:53]
	v_mfma_f32_16x16x32_bf16 v[38:41], v[176:179], v[226:229], v[38:41]
	v_mfma_f32_16x16x32_bf16 v[34:37], v[184:187], v[226:229], v[34:37]
	v_mfma_f32_16x16x32_bf16 v[22:25], v[176:179], v[234:237], v[22:25]
	v_mfma_f32_16x16x32_bf16 v[18:21], v[184:187], v[234:237], v[18:21]
	v_mfma_f32_16x16x32_bf16 v[6:9], v[176:179], v[242:245], v[6:9]
	v_mfma_f32_16x16x32_bf16 v[2:5], v[184:187], v[242:245], v[2:5]
	s_nop 0
	s_barrier
	s_add_i32 s50, 0, 0x18000
	v_add_u32_e32 v0, s50, v163
	s_add_i32 s51, 0, 0x1c000
	ds_read_b128 v[148:151], v0
	ds_read_b128 v[152:155], v0 offset:1024
	ds_read_b128 v[156:159], v0 offset:2048
	ds_read_b128 v[168:171], v0 offset:3072
	v_add_u32_e32 v0, s51, v163
	ds_read_b128 v[172:175], v0
	ds_read_b128 v[176:179], v0 offset:1024
	ds_read_b128 v[180:183], v0 offset:2048
	ds_read_b128 v[184:187], v0 offset:3072
	s_add_u32 s26, s26, 0x40000
	s_addc_u32 s27, s27, 0
	s_mov_b32 m0, s35
	v_lshl_add_u64 v[248:249], s[26:27], 0, v[136:137]
	ds_read_b128 v[188:191], v166 offset:32768
	ds_read_b128 v[206:209], v166 offset:33792
	ds_read_b128 v[222:225], v166 offset:34816
	ds_read_b128 v[226:229], v166 offset:35840
	ds_read_b128 v[230:233], v166 offset:36864
	ds_read_b128 v[234:237], v166 offset:37888
	ds_read_b128 v[238:241], v166 offset:38912
	ds_read_b128 v[242:245], v166 offset:39936
	global_load_lds_dwordx4 v[248:249], off
	v_lshl_add_u64 v[248:249], s[26:27], 0, v[132:133]
	s_mov_b32 m0, s36
	s_nop 0
	global_load_lds_dwordx4 v[248:249], off
	s_waitcnt vmcnt(8)
	s_waitcnt lgkmcnt(0)
	s_barrier
	s_nop 0
	s_waitcnt lgkmcnt(0)
	v_mfma_f32_16x16x32_bf16 v[126:129], v[148:151], v[188:191], v[126:129]
	v_mfma_f32_16x16x32_bf16 v[122:125], v[156:159], v[188:191], v[122:125]
	v_mfma_f32_16x16x32_bf16 v[110:113], v[148:151], v[222:225], v[110:113]
	v_mfma_f32_16x16x32_bf16 v[106:109], v[156:159], v[222:225], v[106:109]
	v_mfma_f32_16x16x32_bf16 v[94:97], v[148:151], v[230:233], v[94:97]
	v_mfma_f32_16x16x32_bf16 v[90:93], v[156:159], v[230:233], v[90:93]
	v_mfma_f32_16x16x32_bf16 v[78:81], v[148:151], v[238:241], v[78:81]
	v_mfma_f32_16x16x32_bf16 v[74:77], v[156:159], v[238:241], v[74:77]
	v_mfma_f32_16x16x32_bf16 v[126:129], v[152:155], v[206:209], v[126:129]
	v_mfma_f32_16x16x32_bf16 v[122:125], v[168:171], v[206:209], v[122:125]
	v_mfma_f32_16x16x32_bf16 v[110:113], v[152:155], v[226:229], v[110:113]
	v_mfma_f32_16x16x32_bf16 v[106:109], v[168:171], v[226:229], v[106:109]
	v_mfma_f32_16x16x32_bf16 v[94:97], v[152:155], v[234:237], v[94:97]
	v_mfma_f32_16x16x32_bf16 v[90:93], v[168:171], v[234:237], v[90:93]
	v_mfma_f32_16x16x32_bf16 v[78:81], v[152:155], v[242:245], v[78:81]
	v_mfma_f32_16x16x32_bf16 v[74:77], v[168:171], v[242:245], v[74:77]
	s_nop 0
	s_nop 0
	v_mfma_f32_16x16x32_bf16 v[118:121], v[172:175], v[188:191], v[118:121]
	v_mfma_f32_16x16x32_bf16 v[114:117], v[180:183], v[188:191], v[114:117]
	v_mfma_f32_16x16x32_bf16 v[102:105], v[172:175], v[222:225], v[102:105]
	v_mfma_f32_16x16x32_bf16 v[98:101], v[180:183], v[222:225], v[98:101]
	v_mfma_f32_16x16x32_bf16 v[86:89], v[172:175], v[230:233], v[86:89]
	v_mfma_f32_16x16x32_bf16 v[82:85], v[180:183], v[230:233], v[82:85]
	v_mfma_f32_16x16x32_bf16 v[70:73], v[172:175], v[238:241], v[70:73]
	v_mfma_f32_16x16x32_bf16 v[66:69], v[180:183], v[238:241], v[66:69]
	v_mfma_f32_16x16x32_bf16 v[118:121], v[176:179], v[206:209], v[118:121]
	v_mfma_f32_16x16x32_bf16 v[114:117], v[184:187], v[206:209], v[114:117]
	v_mfma_f32_16x16x32_bf16 v[102:105], v[176:179], v[226:229], v[102:105]
	v_mfma_f32_16x16x32_bf16 v[98:101], v[184:187], v[226:229], v[98:101]
	v_mfma_f32_16x16x32_bf16 v[86:89], v[176:179], v[234:237], v[86:89]
	v_mfma_f32_16x16x32_bf16 v[82:85], v[184:187], v[234:237], v[82:85]
	v_mfma_f32_16x16x32_bf16 v[70:73], v[176:179], v[242:245], v[70:73]
	v_mfma_f32_16x16x32_bf16 v[66:69], v[184:187], v[242:245], v[66:69]
	s_nop 0
	s_barrier
; #define PG8_STAGE(bufoff, gbase, voff) do { _Pragma("unroll") for (int _i = 0; _i < 2; ++_i) \
;         __builtin_amdgcn_global_load_lds((const unsigned*)((const char*)(gbase) + (voff)[_i]), (PG8_LAS unsigned*)(lds + (bufoff) + ldsw + _i * 8192), 16, 0, 0); } while (0)
; #define PG8_LDA(dst, b, h) do { _Pragma("unroll") for (int m = 0; m < 4; ++m) _Pragma("unroll") for (int k = 0; k < 2; ++k) dst[m][k] = *(const PG8_LAS bf16x8*)(lds + PG8_SA(b, h) + aoff + m * 2048 + k * 1024); } while (0)
; #define PG8_MMA(ai, bj, At, Bt) do { __builtin_amdgcn_s_setprio(1); _Pragma("unroll") for (int m = 0; m < 4; ++m) _Pragma("unroll") for (int n = 0; n < 2; ++n) _Pragma("unroll") for (int k = 0; k < 2; ++k) \
;         acc[ai][bj][m][n] = __builtin_amdgcn_mfma_f32_16x16x32_bf16(Bt[n][k], At[m][k], acc[ai][bj][m][n], 0, 0, 0); __builtin_amdgcn_s_setprio(0); } while (0)
; #define PG8_WAIT_V(n) asm volatile("s_waitcnt vmcnt(" #n ")" ::: "memory")
; #define PG8_WAIT_L(n) asm volatile("s_waitcnt lgkmcnt(" #n ")" ::: "memory")
; #define PG8_BAR __builtin_amdgcn_s_barrier()
; #define PG8_SCHED __builtin_amdgcn_sched_barrier(0)
; template <class Epi, class Sched, bool ALIGN_EPI = false, bool SP2 = false>
; __device__ __forceinline__ void gemm_phase(PG8_LAS unsigned char* lds, const Gemm g, const Sched& S, const Epi& E) {
;     ...
;         for (int t = 0; t < nt; t += 2) {
;             const bool last = (t == nt - 2);
;     ...
;             PG8_LDA(At, 1, 1); PG8_STAGE(PG8_SB(1, 0), b3, voffB); PG8_STAGE(PG8_SB(1, 1), b3 + hstep, voffB); PG8_STAGE(PG8_SA(1, 0), a3, voffA);
;             PG8_WAIT_V(8); PG8_WAIT_L(0); PG8_BAR; PG8_MMA(1, 0, At, B0); PG8_MMA(1, 1, At, B1); PG8_BAR; PG8_SCHED;
	s_add_i32 s26, s50, s31
	v_lshl_add_u64 v[160:161], v[160:161], 0, s[96:97]
	s_mov_b32 m0, s26
	ds_read_b128 v[188:191], v166 offset:49152
	ds_read_b128 v[206:209], v166 offset:50176
	ds_read_b128 v[222:225], v166 offset:51200
	ds_read_b128 v[226:229], v166 offset:52224
	ds_read_b128 v[230:233], v166 offset:53248
	ds_read_b128 v[234:237], v166 offset:54272
	ds_read_b128 v[238:241], v166 offset:55296
	ds_read_b128 v[242:245], v166 offset:56320
	global_load_lds_dwordx4 v[160:161], off
	s_add_i32 m0, s26, 0x2000
	s_add_u32 s8, s8, 0x40080
	v_lshl_add_u64 v[160:161], v[164:165], 0, s[96:97]
	s_addc_u32 s9, s9, 0
	s_add_i32 s26, s51, s31
	global_load_lds_dwordx4 v[160:161], off
	v_lshl_add_u64 v[160:161], s[8:9], 0, v[134:135]
	s_mov_b32 m0, s26
	s_nop 0
	global_load_lds_dwordx4 v[160:161], off
	v_lshl_add_u64 v[160:161], s[8:9], 0, v[130:131]
	s_add_i32 m0, s26, 0x2000
	s_nop 0
	global_load_lds_dwordx4 v[160:161], off
	v_lshl_add_u64 v[160:161], v[192:193], 0, s[96:97]
	s_mov_b32 m0, s39
	s_nop 0
	global_load_lds_dwordx4 v[160:161], off
	v_lshl_add_u64 v[160:161], v[246:247], 0, s[96:97]
	s_mov_b32 m0, s40
	s_nop 0
	global_load_lds_dwordx4 v[160:161], off
	s_waitcnt vmcnt(8)
	s_waitcnt lgkmcnt(0)
	s_barrier
	s_nop 0
	s_waitcnt lgkmcnt(0)
	v_mfma_f32_16x16x32_bf16 v[62:65], v[148:151], v[188:191], v[62:65]
	v_mfma_f32_16x16x32_bf16 v[58:61], v[156:159], v[188:191], v[58:61]
	v_mfma_f32_16x16x32_bf16 v[46:49], v[148:151], v[222:225], v[46:49]
	v_mfma_f32_16x16x32_bf16 v[42:45], v[156:159], v[222:225], v[42:45]
	v_mfma_f32_16x16x32_bf16 v[30:33], v[148:151], v[230:233], v[30:33]
	v_mfma_f32_16x16x32_bf16 v[26:29], v[156:159], v[230:233], v[26:29]
	v_mfma_f32_16x16x32_bf16 v[14:17], v[148:151], v[238:241], v[14:17]
	v_mfma_f32_16x16x32_bf16 v[10:13], v[156:159], v[238:241], v[10:13]
	v_mfma_f32_16x16x32_bf16 v[62:65], v[152:155], v[206:209], v[62:65]
	v_mfma_f32_16x16x32_bf16 v[58:61], v[168:171], v[206:209], v[58:61]
	v_mfma_f32_16x16x32_bf16 v[46:49], v[152:155], v[226:229], v[46:49]
	v_mfma_f32_16x16x32_bf16 v[42:45], v[168:171], v[226:229], v[42:45]
	v_mfma_f32_16x16x32_bf16 v[30:33], v[152:155], v[234:237], v[30:33]
	v_mfma_f32_16x16x32_bf16 v[26:29], v[168:171], v[234:237], v[26:29]
	v_mfma_f32_16x16x32_bf16 v[14:17], v[152:155], v[242:245], v[14:17]
	v_mfma_f32_16x16x32_bf16 v[10:13], v[168:171], v[242:245], v[10:13]
	s_nop 0
	s_nop 0
	v_mfma_f32_16x16x32_bf16 v[54:57], v[172:175], v[188:191], v[54:57]
	v_mfma_f32_16x16x32_bf16 v[50:53], v[180:183], v[188:191], v[50:53]
	v_mfma_f32_16x16x32_bf16 v[38:41], v[172:175], v[222:225], v[38:41]
	v_mfma_f32_16x16x32_bf16 v[34:37], v[180:183], v[222:225], v[34:37]
	v_mfma_f32_16x16x32_bf16 v[22:25], v[172:175], v[230:233], v[22:25]
	v_mfma_f32_16x16x32_bf16 v[18:21], v[180:183], v[230:233], v[18:21]
	v_mfma_f32_16x16x32_bf16 v[6:9], v[172:175], v[238:241], v[6:9]
	v_mfma_f32_16x16x32_bf16 v[2:5], v[180:183], v[238:241], v[2:5]
	v_mfma_f32_16x16x32_bf16 v[54:57], v[176:179], v[206:209], v[54:57]
	v_mfma_f32_16x16x32_bf16 v[50:53], v[184:187], v[206:209], v[50:53]
	v_mfma_f32_16x16x32_bf16 v[38:41], v[176:179], v[226:229], v[38:41]
	v_mfma_f32_16x16x32_bf16 v[34:37], v[184:187], v[226:229], v[34:37]
	v_mfma_f32_16x16x32_bf16 v[22:25], v[176:179], v[234:237], v[22:25]
	v_mfma_f32_16x16x32_bf16 v[18:21], v[184:187], v[234:237], v[18:21]
	v_mfma_f32_16x16x32_bf16 v[6:9], v[176:179], v[242:245], v[6:9]
	v_mfma_f32_16x16x32_bf16 v[2:5], v[184:187], v[242:245], v[2:5]
	s_nop 0
	s_barrier
	s_add_i32 s49, s49, 2
	s_add_u32 s47, s47, 0x100
	s_addc_u32 s48, s48, 0
	s_add_u32 s0, s0, 0x100
	s_addc_u32 s1, s1, 0
	s_cmp_gt_u32 s49, 13
	s_cbranch_scc0 .LBB0_140
	s_and_b64 vcc, exec, s[14:15]
	s_cbranch_vccz .LBB0_143
	s_barrier

; #define PG8_WAIT_V(n) asm volatile("s_waitcnt vmcnt(" #n ")" ::: "memory")
; #define PG8_BAR __builtin_amdgcn_s_barrier()
; template <class Epi, class Sched, bool ALIGN_EPI = false, bool SP2 = false>
; __device__ __forceinline__ void gemm_phase(PG8_LAS unsigned char* lds, const Gemm g, const Sched& S, const Epi& E) {
;     ...
;     PG8_WAIT_V(0);
;     if constexpr (!ALIGN_EPI) { if (wr == 0) PG8_BAR; }
;     PG8_BAR;
.LBB0_194:
	s_setprio 0
	s_waitcnt vmcnt(0)
	s_mov_b32 s37, 0x7f800000
	s_movk_i32 s38, 0x5ff
	s_mov_b32 s40, 0xbfb8aa3b
	s_barrier

; #define PG8_STAGE(bufoff, gbase, voff) do { _Pragma("unroll") for (int _i = 0; _i < 2; ++_i) \
;         __builtin_amdgcn_global_load_lds((const unsigned*)((const char*)(gbase) + (voff)[_i]), (PG8_LAS unsigned*)(lds + (bufoff) + ldsw + _i * 8192), 16, 0, 0); } while (0)
; #define PG8_WAIT_V(n) asm volatile("s_waitcnt vmcnt(" #n ")" ::: "memory")
; #define PG8_BAR __builtin_amdgcn_s_barrier()
; template <class Epi, class Sched, bool ALIGN_EPI = false, bool SP2 = false>
; __device__ __forceinline__ void gemm_phase(PG8_LAS unsigned char* lds, const Gemm g, const Sched& S, const Epi& E) {
;     ...
;     const int tid = tid_, wid = __builtin_amdgcn_readfirstlane(tid >> 6), lane = tid & 63, wr = wid >> 2, wc = wid & 3, fr = lane & 15, fq = lane >> 4;
;     const int K = g.K, nt = K / BK;
;     unsigned voffA[2], voffB[2];
; #pragma unroll
;     for (int i = 0; i < 2; ++i) { int R, C; stage_rc(tid * 16 + i * 8192, R, C); const int Rb = Epi::PERM ? ((R & ~31) + perm32(R & 31)) : R;
;         voffA[i] = (unsigned)(R * K + C) * 2u; voffB[i] = (unsigned)(Rb * K + C) * 2u; }
;     const size_t kstep = (size_t)(BK * 2);
;     const size_t hstep = (size_t)HALF * K * 2;
;     const size_t tstep = 2 * hstep;
;     const unsigned ldsw = (unsigned)wid * 1024u;
;     const int aoff = lds_byte(wr * 64 + fr, fq * 8), boff = lds_byte(wc * 32 + fr, fq * 8);
;     ...
;         PG8_STAGE(PG8_SB(1, 0), cB + kstep, voffB); PG8_STAGE(PG8_SA(1, 0), cA + kstep, voffA); PG8_STAGE(PG8_SB(1, 1), cB + hstep + kstep, voffB);
;         PG8_WAIT_V(6); PG8_BAR;
.LBB0_368:
	s_add_u32 s14, s2, 0x6a00000
	s_addc_u32 s15, s3, 0
	s_lshl_b32 s6, s6, 5
	s_and_b32 s40, s6, 0x60
	s_add_i32 m0, s36, 0x18000
	v_lshl_add_u64 v[8:9], v[8:9], 0, s[96:97]
	s_lshl_b32 s16, s5, 13
	s_lshl_b32 s17, s40, 7
	s_waitcnt vmcnt(2)
	s_barrier
	global_load_lds_dwordx4 v[8:9], off
	v_lshl_add_u64 v[6:7], v[6:7], 0, s[96:97]
	s_add_i32 m0, s36, 0x1a000
	s_add_i32 s41, s36, 0x8000
	s_add_i32 s42, s36, 0xa000
	global_load_lds_dwordx4 v[6:7], off
	v_lshl_add_u64 v[2:3], v[2:3], 0, s[96:97]
	s_mov_b32 m0, s41
	s_add_u32 s6, s0, 0x40080
	global_load_lds_dwordx4 v[2:3], off
	v_lshl_add_u64 v[2:3], v[4:5], 0, s[96:97]
	s_mov_b32 m0, s42
	s_addc_u32 s7, s1, 0
	global_load_lds_dwordx4 v[2:3], off
	s_add_i32 m0, s36, 0x1c000
	v_lshl_add_u64 v[2:3], s[6:7], 0, v[134:135]
	global_load_lds_dwordx4 v[2:3], off
	v_lshl_add_u64 v[2:3], s[6:7], 0, v[130:131]
	s_add_i32 m0, s36, 0x1e000
	s_cmpk_lt_u32 s4, 0x100
	global_load_lds_dwordx4 v[2:3], off
	v_bfe_u32 v2, v0, 4, 2
	v_and_b32_e32 v3, 15, v0
	v_lshlrev_b32_e32 v138, 3, v2
	v_lshlrev_b32_e32 v2, 4, v2
	v_lshlrev_b32_e32 v0, 2, v0
	v_lshl_or_b32 v139, s5, 6, v3
	v_lshl_or_b32 v3, v3, 6, v2
	v_and_b32_e32 v0, 32, v0
	v_bitop3_b32 v6, v3, s16, v0 bitop3:0xde
	v_bitop3_b32 v163, v3, s17, v0 bitop3:0xde
	v_or_b32_e32 v0, s40, v138
	v_cmp_gt_u32_e64 s[6:7], s72, v0
	v_lshlrev_b32_e32 v0, 2, v0
	v_lshl_add_u64 v[4:5], s[2:3], 0, v[0:1]
	s_mov_b64 s[4:5], 0x16e00000
	v_mov_b32_e32 v3, v1
	v_lshlrev_b32_e32 v0, 14, v10
	v_lshl_add_u64 v[140:141], v[4:5], 0, s[4:5]
	v_lshl_add_u64 v[2:3], s[2:3], 0, v[2:3]
	s_mov_b64 s[4:5], 0x1b800000
	v_and_b32_e32 v0, 0xffff8000, v0
	v_lshl_add_u64 v[142:143], v[2:3], 0, s[4:5]
	v_lshl_add_u32 v0, v11, 11, v0
	v_and_b32_e32 v2, 1, v10
	v_lshl_or_b32 v0, v2, 6, v0
	v_lshl_add_u32 v144, v12, 1, v0
	v_lshlrev_b32_e32 v0, 14, v14
	v_and_b32_e32 v0, 0xffff8000, v0
	s_waitcnt vmcnt(6)
	v_lshl_add_u32 v0, v13, 11, v0
	v_and_b32_e32 v2, 1, v14
	v_lshl_or_b32 v0, v2, 6, v0
	v_readlane_b32 s4, v254, 13
	s_cselect_b64 s[16:17], -1, 0
	s_waitcnt lgkmcnt(0)
	s_ashr_i32 s43, s30, 31
	v_mov_b32_e32 v145, v1
	v_lshl_add_u32 v146, v15, 1, v0
	v_mov_b32_e32 v147, v1
	s_mov_b32 s44, 0
	v_add_u32_e32 v166, 0, v6
	v_readlane_b32 s45, v253, 63
	s_mov_b32 s46, s4
	s_barrier
	v_readlane_b32 s5, v254, 14
	v_readfirstlane_b32 s100, v210
	s_nop 3
	s_lshr_b32 s100, s100, 6
	s_cmp_lt_u32 s100, 4
	s_cbranch_scc1 .Lgp_g2
	s_setprio 1

; #define PG8_STAGE(bufoff, gbase, voff) do { _Pragma("unroll") for (int _i = 0; _i < 2; ++_i) \
;         __builtin_amdgcn_global_load_lds((const unsigned*)((const char*)(gbase) + (voff)[_i]), (PG8_LAS unsigned*)(lds + (bufoff) + ldsw + _i * 8192), 16, 0, 0); } while (0)
; #define PG8_LDA(dst, b, h) do { _Pragma("unroll") for (int m = 0; m < 4; ++m) _Pragma("unroll") for (int k = 0; k < 2; ++k) dst[m][k] = *(const PG8_LAS bf16x8*)(lds + PG8_SA(b, h) + aoff + m * 2048 + k * 1024); } while (0)
; #define PG8_LDB(dst, b, h) do { _Pragma("unroll") for (int n = 0; n < 2; ++n) _Pragma("unroll") for (int k = 0; k < 2; ++k) dst[n][k] = *(const PG8_LAS bf16x8*)(lds + PG8_SB(b, h) + boff + n * 2048 + k * 1024); } while (0)
; #define PG8_MMA(ai, bj, At, Bt) do { __builtin_amdgcn_s_setprio(1); _Pragma("unroll") for (int m = 0; m < 4; ++m) _Pragma("unroll") for (int n = 0; n < 2; ++n) _Pragma("unroll") for (int k = 0; k < 2; ++k) \
;         acc[ai][bj][m][n] = __builtin_amdgcn_mfma_f32_16x16x32_bf16(Bt[n][k], At[m][k], acc[ai][bj][m][n], 0, 0, 0); __builtin_amdgcn_s_setprio(0); } while (0)
; #define PG8_WAIT_V(n) asm volatile("s_waitcnt vmcnt(" #n ")" ::: "memory")
; #define PG8_WAIT_L(n) asm volatile("s_waitcnt lgkmcnt(" #n ")" ::: "memory")
; #define PG8_BAR __builtin_amdgcn_s_barrier()
; #define PG8_SCHED __builtin_amdgcn_sched_barrier(0)
; template <class Epi, class Sched, bool ALIGN_EPI = false, bool SP2 = false>
; __device__ __forceinline__ void gemm_phase(PG8_LAS unsigned char* lds, const Gemm g, const Sched& S, const Epi& E) {
;     ...
;             PG8_LDB(B0, 0, 0); PG8_LDB(B1, 0, 1); PG8_SCHED; PG8_LDA(At, 0, 0); PG8_STAGE(PG8_SA(1, 1), a1 + hstep, voffA);
;             PG8_WAIT_V(8); PG8_WAIT_L(0); PG8_BAR; PG8_MMA(0, 0, At, B0); PG8_MMA(0, 1, At, B1); PG8_BAR; PG8_SCHED;
;             PG8_LDA(At, 0, 1); PG8_STAGE(PG8_SB(0, 0), b2, voffB); PG8_STAGE(PG8_SB(0, 1), b2 + hstep, voffB); PG8_STAGE(PG8_SA(0, 0), a2, voffA);
;             PG8_WAIT_V(8); PG8_WAIT_L(0); PG8_BAR; PG8_MMA(1, 0, At, B0); PG8_MMA(1, 1, At, B1); PG8_BAR; PG8_SCHED;
.LBB0_378:
	s_add_u32 s8, s0, 0xfffc0080
	s_addc_u32 s9, s1, -1
	s_add_i32 s52, 0, 0x10000
	s_cmp_eq_u32 s51, 12
	s_cselect_b32 s29, s23, s9
	s_cselect_b32 s28, s47, s8
	v_add_u32_e32 v0, s52, v163
	s_cselect_b32 s9, s19, s50
	s_cselect_b32 s8, s48, s49
	s_add_i32 s54, 0, 0x14000
	ds_read_b128 v[148:151], v0
	ds_read_b128 v[152:155], v0 offset:1024
	ds_read_b128 v[156:159], v0 offset:2048
	ds_read_b128 v[168:171], v0 offset:3072
	v_add_u32_e32 v0, s54, v163
	ds_read_b128 v[172:175], v0
	ds_read_b128 v[176:179], v0 offset:1024
	ds_read_b128 v[180:183], v0 offset:2048
	ds_read_b128 v[184:187], v0 offset:3072
	v_lshl_add_u64 v[160:161], s[0:1], 0, v[146:147]
	s_add_i32 m0, s36, 0xc000
	ds_read_b128 v[188:191], v166
	ds_read_b128 v[206:209], v166 offset:1024
	ds_read_b128 v[222:225], v166 offset:2048
	ds_read_b128 v[226:229], v166 offset:3072
	ds_read_b128 v[230:233], v166 offset:4096
	ds_read_b128 v[234:237], v166 offset:5120
	ds_read_b128 v[238:241], v166 offset:6144
	ds_read_b128 v[242:245], v166 offset:7168
	global_load_lds_dwordx4 v[160:161], off
	v_lshl_add_u64 v[160:161], s[0:1], 0, v[144:145]
	s_add_i32 m0, s36, 0xe000
	s_nop 0
	global_load_lds_dwordx4 v[160:161], off
	s_waitcnt vmcnt(8)
	s_waitcnt lgkmcnt(0)
	s_barrier
	s_nop 0
	s_waitcnt lgkmcnt(0)
	v_mfma_f32_16x16x32_bf16 v[126:129], v[148:151], v[188:191], v[126:129]
	v_mfma_f32_16x16x32_bf16 v[122:125], v[156:159], v[188:191], v[122:125]
	v_mfma_f32_16x16x32_bf16 v[110:113], v[148:151], v[222:225], v[110:113]
	v_mfma_f32_16x16x32_bf16 v[106:109], v[156:159], v[222:225], v[106:109]
	v_mfma_f32_16x16x32_bf16 v[94:97], v[148:151], v[230:233], v[94:97]
	v_mfma_f32_16x16x32_bf16 v[90:93], v[156:159], v[230:233], v[90:93]
	v_mfma_f32_16x16x32_bf16 v[78:81], v[148:151], v[238:241], v[78:81]
	v_mfma_f32_16x16x32_bf16 v[74:77], v[156:159], v[238:241], v[74:77]
	v_mfma_f32_16x16x32_bf16 v[126:129], v[152:155], v[206:209], v[126:129]
	v_mfma_f32_16x16x32_bf16 v[122:125], v[168:171], v[206:209], v[122:125]
	v_mfma_f32_16x16x32_bf16 v[110:113], v[152:155], v[226:229], v[110:113]
	v_mfma_f32_16x16x32_bf16 v[106:109], v[168:171], v[226:229], v[106:109]
	v_mfma_f32_16x16x32_bf16 v[94:97], v[152:155], v[234:237], v[94:97]
	v_mfma_f32_16x16x32_bf16 v[90:93], v[168:171], v[234:237], v[90:93]
	v_mfma_f32_16x16x32_bf16 v[78:81], v[152:155], v[242:245], v[78:81]
	v_mfma_f32_16x16x32_bf16 v[74:77], v[168:171], v[242:245], v[74:77]
	s_nop 0
	s_nop 0
	v_mfma_f32_16x16x32_bf16 v[118:121], v[172:175], v[188:191], v[118:121]
	v_mfma_f32_16x16x32_bf16 v[114:117], v[180:183], v[188:191], v[114:117]
	v_mfma_f32_16x16x32_bf16 v[102:105], v[172:175], v[222:225], v[102:105]
	v_mfma_f32_16x16x32_bf16 v[98:101], v[180:183], v[222:225], v[98:101]
	v_mfma_f32_16x16x32_bf16 v[86:89], v[172:175], v[230:233], v[86:89]
	v_mfma_f32_16x16x32_bf16 v[82:85], v[180:183], v[230:233], v[82:85]
	v_mfma_f32_16x16x32_bf16 v[70:73], v[172:175], v[238:241], v[70:73]
	v_mfma_f32_16x16x32_bf16 v[66:69], v[180:183], v[238:241], v[66:69]
	v_mfma_f32_16x16x32_bf16 v[118:121], v[176:179], v[206:209], v[118:121]
	v_mfma_f32_16x16x32_bf16 v[114:117], v[184:187], v[206:209], v[114:117]
	v_mfma_f32_16x16x32_bf16 v[102:105], v[176:179], v[226:229], v[102:105]
	v_mfma_f32_16x16x32_bf16 v[98:101], v[184:187], v[226:229], v[98:101]
	v_mfma_f32_16x16x32_bf16 v[86:89], v[176:179], v[234:237], v[86:89]
	v_mfma_f32_16x16x32_bf16 v[82:85], v[184:187], v[234:237], v[82:85]
	v_mfma_f32_16x16x32_bf16 v[70:73], v[176:179], v[242:245], v[70:73]
	v_mfma_f32_16x16x32_bf16 v[66:69], v[184:187], v[242:245], v[66:69]
	s_nop 0
	s_barrier
	s_add_i32 s52, s52, s35
	v_lshl_add_u64 v[160:161], s[8:9], 0, v[134:135]
	s_mov_b32 m0, s52
	ds_read_b128 v[188:191], v166 offset:16384
	ds_read_b128 v[206:209], v166 offset:17408
	ds_read_b128 v[222:225], v166 offset:18432
	ds_read_b128 v[226:229], v166 offset:19456
	ds_read_b128 v[230:233], v166 offset:20480
	ds_read_b128 v[234:237], v166 offset:21504
	ds_read_b128 v[238:241], v166 offset:22528
	ds_read_b128 v[242:245], v166 offset:23552
	global_load_lds_dwordx4 v[160:161], off
	s_add_i32 m0, s52, 0x2000
	s_add_u32 s52, s8, 0x40000
	v_lshl_add_u64 v[164:165], s[8:9], 0, v[130:131]
	s_addc_u32 s53, s9, 0
	s_add_i32 s54, s54, s35
	global_load_lds_dwordx4 v[164:165], off
	v_lshl_add_u64 v[192:193], s[52:53], 0, v[134:135]
	s_mov_b32 m0, s54
	v_lshl_add_u64 v[246:247], s[28:29], 0, v[132:133]
	global_load_lds_dwordx4 v[192:193], off
	v_lshl_add_u64 v[192:193], s[52:53], 0, v[130:131]
	s_add_i32 m0, s54, 0x2000
	s_nop 0
	global_load_lds_dwordx4 v[192:193], off
	v_lshl_add_u64 v[192:193], s[28:29], 0, v[136:137]
	s_mov_b32 m0, s36
	s_nop 0
	global_load_lds_dwordx4 v[192:193], off
	s_mov_b32 m0, s37
	s_nop 0
	global_load_lds_dwordx4 v[246:247], off
	s_waitcnt vmcnt(8)
	s_waitcnt lgkmcnt(0)
	s_barrier
; #define PG8_STAGE(bufoff, gbase, voff) do { _Pragma("unroll") for (int _i = 0; _i < 2; ++_i) \
;         __builtin_amdgcn_global_load_lds((const unsigned*)((const char*)(gbase) + (voff)[_i]), (PG8_LAS unsigned*)(lds + (bufoff) + ldsw + _i * 8192), 16, 0, 0); } while (0)
; #define PG8_LDA(dst, b, h) do { _Pragma("unroll") for (int m = 0; m < 4; ++m) _Pragma("unroll") for (int k = 0; k < 2; ++k) dst[m][k] = *(const PG8_LAS bf16x8*)(lds + PG8_SA(b, h) + aoff + m * 2048 + k * 1024); } while (0)
; #define PG8_LDB(dst, b, h) do { _Pragma("unroll") for (int n = 0; n < 2; ++n) _Pragma("unroll") for (int k = 0; k < 2; ++k) dst[n][k] = *(const PG8_LAS bf16x8*)(lds + PG8_SB(b, h) + boff + n * 2048 + k * 1024); } while (0)
; #define PG8_MMA(ai, bj, At, Bt) do { __builtin_amdgcn_s_setprio(1); _Pragma("unroll") for (int m = 0; m < 4; ++m) _Pragma("unroll") for (int n = 0; n < 2; ++n) _Pragma("unroll") for (int k = 0; k < 2; ++k) \
;         acc[ai][bj][m][n] = __builtin_amdgcn_mfma_f32_16x16x32_bf16(Bt[n][k], At[m][k], acc[ai][bj][m][n], 0, 0, 0); __builtin_amdgcn_s_setprio(0); } while (0)
; #define PG8_WAIT_V(n) asm volatile("s_waitcnt vmcnt(" #n ")" ::: "memory")
; #define PG8_WAIT_L(n) asm volatile("s_waitcnt lgkmcnt(" #n ")" ::: "memory")
; #define PG8_BAR __builtin_amdgcn_s_barrier()
; #define PG8_SCHED __builtin_amdgcn_sched_barrier(0)
; template <class Epi, class Sched, bool ALIGN_EPI = false, bool SP2 = false>
; __device__ __forceinline__ void gemm_phase(PG8_LAS unsigned char* lds, const Gemm g, const Sched& S, const Epi& E) {
;     ...
;             PG8_WAIT_V(8); PG8_WAIT_L(0); PG8_BAR; PG8_MMA(1, 0, At, B0); PG8_MMA(1, 1, At, B1); PG8_BAR; PG8_SCHED;
;             PG8_LDB(B0, 1, 0); PG8_LDB(B1, 1, 1); PG8_SCHED; PG8_LDA(At, 1, 0); PG8_STAGE(PG8_SA(0, 1), a2 + hstep, voffA);
;             PG8_WAIT_V(8); PG8_WAIT_L(0); PG8_BAR; PG8_MMA(0, 0, At, B0); PG8_MMA(0, 1, At, B1); PG8_BAR; PG8_SCHED;
	s_nop 0
	s_waitcnt lgkmcnt(0)
	v_mfma_f32_16x16x32_bf16 v[62:65], v[148:151], v[188:191], v[62:65]
	v_mfma_f32_16x16x32_bf16 v[58:61], v[156:159], v[188:191], v[58:61]
	v_mfma_f32_16x16x32_bf16 v[46:49], v[148:151], v[222:225], v[46:49]
	v_mfma_f32_16x16x32_bf16 v[42:45], v[156:159], v[222:225], v[42:45]
	v_mfma_f32_16x16x32_bf16 v[30:33], v[148:151], v[230:233], v[30:33]
	v_mfma_f32_16x16x32_bf16 v[26:29], v[156:159], v[230:233], v[26:29]
	v_mfma_f32_16x16x32_bf16 v[14:17], v[148:151], v[238:241], v[14:17]
	v_mfma_f32_16x16x32_bf16 v[10:13], v[156:159], v[238:241], v[10:13]
	v_mfma_f32_16x16x32_bf16 v[62:65], v[152:155], v[206:209], v[62:65]
	v_mfma_f32_16x16x32_bf16 v[58:61], v[168:171], v[206:209], v[58:61]
	v_mfma_f32_16x16x32_bf16 v[46:49], v[152:155], v[226:229], v[46:49]
	v_mfma_f32_16x16x32_bf16 v[42:45], v[168:171], v[226:229], v[42:45]
	v_mfma_f32_16x16x32_bf16 v[30:33], v[152:155], v[234:237], v[30:33]
	v_mfma_f32_16x16x32_bf16 v[26:29], v[168:171], v[234:237], v[26:29]
	v_mfma_f32_16x16x32_bf16 v[14:17], v[152:155], v[242:245], v[14:17]
	v_mfma_f32_16x16x32_bf16 v[10:13], v[168:171], v[242:245], v[10:13]
	s_nop 0
	s_nop 0
	v_mfma_f32_16x16x32_bf16 v[54:57], v[172:175], v[188:191], v[54:57]
	v_mfma_f32_16x16x32_bf16 v[50:53], v[180:183], v[188:191], v[50:53]
	v_mfma_f32_16x16x32_bf16 v[38:41], v[172:175], v[222:225], v[38:41]
	v_mfma_f32_16x16x32_bf16 v[34:37], v[180:183], v[222:225], v[34:37]
	v_mfma_f32_16x16x32_bf16 v[22:25], v[172:175], v[230:233], v[22:25]
	v_mfma_f32_16x16x32_bf16 v[18:21], v[180:183], v[230:233], v[18:21]
	v_mfma_f32_16x16x32_bf16 v[6:9], v[172:175], v[238:241], v[6:9]
	v_mfma_f32_16x16x32_bf16 v[2:5], v[180:183], v[238:241], v[2:5]
	v_mfma_f32_16x16x32_bf16 v[54:57], v[176:179], v[206:209], v[54:57]
	v_mfma_f32_16x16x32_bf16 v[50:53], v[184:187], v[206:209], v[50:53]
	v_mfma_f32_16x16x32_bf16 v[38:41], v[176:179], v[226:229], v[38:41]
	v_mfma_f32_16x16x32_bf16 v[34:37], v[184:187], v[226:229], v[34:37]
	v_mfma_f32_16x16x32_bf16 v[22:25], v[176:179], v[234:237], v[22:25]
	v_mfma_f32_16x16x32_bf16 v[18:21], v[184:187], v[234:237], v[18:21]
	v_mfma_f32_16x16x32_bf16 v[6:9], v[176:179], v[242:245], v[6:9]
	v_mfma_f32_16x16x32_bf16 v[2:5], v[184:187], v[242:245], v[2:5]
	s_nop 0
	s_barrier
	s_add_i32 s52, 0, 0x18000
	v_add_u32_e32 v0, s52, v163
	s_add_i32 s53, 0, 0x1c000
	ds_read_b128 v[148:151], v0
	ds_read_b128 v[152:155], v0 offset:1024
	ds_read_b128 v[156:159], v0 offset:2048
	ds_read_b128 v[168:171], v0 offset:3072
	v_add_u32_e32 v0, s53, v163
	ds_read_b128 v[172:175], v0
	ds_read_b128 v[176:179], v0 offset:1024
	ds_read_b128 v[180:183], v0 offset:2048
	ds_read_b128 v[184:187], v0 offset:3072
	s_add_u32 s28, s28, 0x40000
	s_addc_u32 s29, s29, 0
	s_mov_b32 m0, s38
	v_lshl_add_u64 v[248:249], s[28:29], 0, v[136:137]
	ds_read_b128 v[188:191], v166 offset:32768
	ds_read_b128 v[206:209], v166 offset:33792
	ds_read_b128 v[222:225], v166 offset:34816
	ds_read_b128 v[226:229], v166 offset:35840
	ds_read_b128 v[230:233], v166 offset:36864
	ds_read_b128 v[234:237], v166 offset:37888
	ds_read_b128 v[238:241], v166 offset:38912
	ds_read_b128 v[242:245], v166 offset:39936
	global_load_lds_dwordx4 v[248:249], off
	v_lshl_add_u64 v[248:249], s[28:29], 0, v[132:133]
	s_mov_b32 m0, s39
	s_nop 0
	global_load_lds_dwordx4 v[248:249], off
	s_waitcnt vmcnt(8)
	s_waitcnt lgkmcnt(0)
	s_barrier
	s_nop 0
	s_waitcnt lgkmcnt(0)
	v_mfma_f32_16x16x32_bf16 v[126:129], v[148:151], v[188:191], v[126:129]
	v_mfma_f32_16x16x32_bf16 v[122:125], v[156:159], v[188:191], v[122:125]
	v_mfma_f32_16x16x32_bf16 v[110:113], v[148:151], v[222:225], v[110:113]
	v_mfma_f32_16x16x32_bf16 v[106:109], v[156:159], v[222:225], v[106:109]
	v_mfma_f32_16x16x32_bf16 v[94:97], v[148:151], v[230:233], v[94:97]
	v_mfma_f32_16x16x32_bf16 v[90:93], v[156:159], v[230:233], v[90:93]
	v_mfma_f32_16x16x32_bf16 v[78:81], v[148:151], v[238:241], v[78:81]
	v_mfma_f32_16x16x32_bf16 v[74:77], v[156:159], v[238:241], v[74:77]
	v_mfma_f32_16x16x32_bf16 v[126:129], v[152:155], v[206:209], v[126:129]
	v_mfma_f32_16x16x32_bf16 v[122:125], v[168:171], v[206:209], v[122:125]
	v_mfma_f32_16x16x32_bf16 v[110:113], v[152:155], v[226:229], v[110:113]
	v_mfma_f32_16x16x32_bf16 v[106:109], v[168:171], v[226:229], v[106:109]
	v_mfma_f32_16x16x32_bf16 v[94:97], v[152:155], v[234:237], v[94:97]
	v_mfma_f32_16x16x32_bf16 v[90:93], v[168:171], v[234:237], v[90:93]
	v_mfma_f32_16x16x32_bf16 v[78:81], v[152:155], v[242:245], v[78:81]
	v_mfma_f32_16x16x32_bf16 v[74:77], v[168:171], v[242:245], v[74:77]
	s_nop 0
	s_nop 0
	v_mfma_f32_16x16x32_bf16 v[118:121], v[172:175], v[188:191], v[118:121]
	v_mfma_f32_16x16x32_bf16 v[114:117], v[180:183], v[188:191], v[114:117]
	v_mfma_f32_16x16x32_bf16 v[102:105], v[172:175], v[222:225], v[102:105]
	v_mfma_f32_16x16x32_bf16 v[98:101], v[180:183], v[222:225], v[98:101]
	v_mfma_f32_16x16x32_bf16 v[86:89], v[172:175], v[230:233], v[86:89]
	v_mfma_f32_16x16x32_bf16 v[82:85], v[180:183], v[230:233], v[82:85]
	v_mfma_f32_16x16x32_bf16 v[70:73], v[172:175], v[238:241], v[70:73]
	v_mfma_f32_16x16x32_bf16 v[66:69], v[180:183], v[238:241], v[66:69]
	v_mfma_f32_16x16x32_bf16 v[118:121], v[176:179], v[206:209], v[118:121]
	v_mfma_f32_16x16x32_bf16 v[114:117], v[184:187], v[206:209], v[114:117]
	v_mfma_f32_16x16x32_bf16 v[102:105], v[176:179], v[226:229], v[102:105]
	v_mfma_f32_16x16x32_bf16 v[98:101], v[184:187], v[226:229], v[98:101]
	v_mfma_f32_16x16x32_bf16 v[86:89], v[176:179], v[234:237], v[86:89]
	v_mfma_f32_16x16x32_bf16 v[82:85], v[184:187], v[234:237], v[82:85]
	v_mfma_f32_16x16x32_bf16 v[70:73], v[176:179], v[242:245], v[70:73]
	v_mfma_f32_16x16x32_bf16 v[66:69], v[184:187], v[242:245], v[66:69]
	s_nop 0
	s_barrier
; #define PG8_STAGE(bufoff, gbase, voff) do { _Pragma("unroll") for (int _i = 0; _i < 2; ++_i) \
;         __builtin_amdgcn_global_load_lds((const unsigned*)((const char*)(gbase) + (voff)[_i]), (PG8_LAS unsigned*)(lds + (bufoff) + ldsw + _i * 8192), 16, 0, 0); } while (0)
; #define PG8_LDA(dst, b, h) do { _Pragma("unroll") for (int m = 0; m < 4; ++m) _Pragma("unroll") for (int k = 0; k < 2; ++k) dst[m][k] = *(const PG8_LAS bf16x8*)(lds + PG8_SA(b, h) + aoff + m * 2048 + k * 1024); } while (0)
; #define PG8_MMA(ai, bj, At, Bt) do { __builtin_amdgcn_s_setprio(1); _Pragma("unroll") for (int m = 0; m < 4; ++m) _Pragma("unroll") for (int n = 0; n < 2; ++n) _Pragma("unroll") for (int k = 0; k < 2; ++k) \
;         acc[ai][bj][m][n] = __builtin_amdgcn_mfma_f32_16x16x32_bf16(Bt[n][k], At[m][k], acc[ai][bj][m][n], 0, 0, 0); __builtin_amdgcn_s_setprio(0); } while (0)
; #define PG8_WAIT_V(n) asm volatile("s_waitcnt vmcnt(" #n ")" ::: "memory")
; #define PG8_WAIT_L(n) asm volatile("s_waitcnt lgkmcnt(" #n ")" ::: "memory")
; #define PG8_BAR __builtin_amdgcn_s_barrier()
; #define PG8_SCHED __builtin_amdgcn_sched_barrier(0)
; template <class Epi, class Sched, bool ALIGN_EPI = false, bool SP2 = false>
; __device__ __forceinline__ void gemm_phase(PG8_LAS unsigned char* lds, const Gemm g, const Sched& S, const Epi& E) {
;     ...
;         for (int t = 0; t < nt; t += 2) {
;             const bool last = (t == nt - 2);
;     ...
;             PG8_LDA(At, 1, 1); PG8_STAGE(PG8_SB(1, 0), b3, voffB); PG8_STAGE(PG8_SB(1, 1), b3 + hstep, voffB); PG8_STAGE(PG8_SA(1, 0), a3, voffA);
;             PG8_WAIT_V(8); PG8_WAIT_L(0); PG8_BAR; PG8_MMA(1, 0, At, B0); PG8_MMA(1, 1, At, B1); PG8_BAR; PG8_SCHED;
	s_add_i32 s28, s52, s35
	v_lshl_add_u64 v[160:161], v[160:161], 0, s[96:97]
	s_mov_b32 m0, s28
	ds_read_b128 v[188:191], v166 offset:49152
	ds_read_b128 v[206:209], v166 offset:50176
	ds_read_b128 v[222:225], v166 offset:51200
	ds_read_b128 v[226:229], v166 offset:52224
	ds_read_b128 v[230:233], v166 offset:53248
	ds_read_b128 v[234:237], v166 offset:54272
	ds_read_b128 v[238:241], v166 offset:55296
	ds_read_b128 v[242:245], v166 offset:56320
	global_load_lds_dwordx4 v[160:161], off
	s_add_i32 m0, s28, 0x2000
	s_add_u32 s8, s8, 0x40080
	v_lshl_add_u64 v[160:161], v[164:165], 0, s[96:97]
	s_addc_u32 s9, s9, 0
	s_add_i32 s28, s53, s35
	global_load_lds_dwordx4 v[160:161], off
	v_lshl_add_u64 v[160:161], s[8:9], 0, v[134:135]
	s_mov_b32 m0, s28
	s_nop 0
	global_load_lds_dwordx4 v[160:161], off
	v_lshl_add_u64 v[160:161], s[8:9], 0, v[130:131]
	s_add_i32 m0, s28, 0x2000
	s_nop 0
	global_load_lds_dwordx4 v[160:161], off
	v_lshl_add_u64 v[160:161], v[192:193], 0, s[96:97]
	s_mov_b32 m0, s41
	s_nop 0
	global_load_lds_dwordx4 v[160:161], off
	v_lshl_add_u64 v[160:161], v[246:247], 0, s[96:97]
	s_mov_b32 m0, s42
	s_nop 0
	global_load_lds_dwordx4 v[160:161], off
	s_waitcnt vmcnt(8)
	s_waitcnt lgkmcnt(0)
	s_barrier
	s_nop 0
	s_waitcnt lgkmcnt(0)
	v_mfma_f32_16x16x32_bf16 v[62:65], v[148:151], v[188:191], v[62:65]
	v_mfma_f32_16x16x32_bf16 v[58:61], v[156:159], v[188:191], v[58:61]
	v_mfma_f32_16x16x32_bf16 v[46:49], v[148:151], v[222:225], v[46:49]
	v_mfma_f32_16x16x32_bf16 v[42:45], v[156:159], v[222:225], v[42:45]
	v_mfma_f32_16x16x32_bf16 v[30:33], v[148:151], v[230:233], v[30:33]
	v_mfma_f32_16x16x32_bf16 v[26:29], v[156:159], v[230:233], v[26:29]
	v_mfma_f32_16x16x32_bf16 v[14:17], v[148:151], v[238:241], v[14:17]
	v_mfma_f32_16x16x32_bf16 v[10:13], v[156:159], v[238:241], v[10:13]
	v_mfma_f32_16x16x32_bf16 v[62:65], v[152:155], v[206:209], v[62:65]
	v_mfma_f32_16x16x32_bf16 v[58:61], v[168:171], v[206:209], v[58:61]
	v_mfma_f32_16x16x32_bf16 v[46:49], v[152:155], v[226:229], v[46:49]
	v_mfma_f32_16x16x32_bf16 v[42:45], v[168:171], v[226:229], v[42:45]
	v_mfma_f32_16x16x32_bf16 v[30:33], v[152:155], v[234:237], v[30:33]
	v_mfma_f32_16x16x32_bf16 v[26:29], v[168:171], v[234:237], v[26:29]
	v_mfma_f32_16x16x32_bf16 v[14:17], v[152:155], v[242:245], v[14:17]
	v_mfma_f32_16x16x32_bf16 v[10:13], v[168:171], v[242:245], v[10:13]
	s_nop 0
	s_nop 0
	v_mfma_f32_16x16x32_bf16 v[54:57], v[172:175], v[188:191], v[54:57]
	v_mfma_f32_16x16x32_bf16 v[50:53], v[180:183], v[188:191], v[50:53]
	v_mfma_f32_16x16x32_bf16 v[38:41], v[172:175], v[222:225], v[38:41]
	v_mfma_f32_16x16x32_bf16 v[34:37], v[180:183], v[222:225], v[34:37]
	v_mfma_f32_16x16x32_bf16 v[22:25], v[172:175], v[230:233], v[22:25]
	v_mfma_f32_16x16x32_bf16 v[18:21], v[180:183], v[230:233], v[18:21]
	v_mfma_f32_16x16x32_bf16 v[6:9], v[172:175], v[238:241], v[6:9]
	v_mfma_f32_16x16x32_bf16 v[2:5], v[180:183], v[238:241], v[2:5]
	v_mfma_f32_16x16x32_bf16 v[54:57], v[176:179], v[206:209], v[54:57]
	v_mfma_f32_16x16x32_bf16 v[50:53], v[184:187], v[206:209], v[50:53]
	v_mfma_f32_16x16x32_bf16 v[38:41], v[176:179], v[226:229], v[38:41]
	v_mfma_f32_16x16x32_bf16 v[34:37], v[184:187], v[226:229], v[34:37]
	v_mfma_f32_16x16x32_bf16 v[22:25], v[176:179], v[234:237], v[22:25]
	v_mfma_f32_16x16x32_bf16 v[18:21], v[184:187], v[234:237], v[18:21]
	v_mfma_f32_16x16x32_bf16 v[6:9], v[176:179], v[242:245], v[6:9]
	v_mfma_f32_16x16x32_bf16 v[2:5], v[184:187], v[242:245], v[2:5]
	s_nop 0
	s_barrier
	s_add_i32 s51, s51, 2
	s_add_u32 s49, s49, 0x100
	s_addc_u32 s50, s50, 0
	s_add_u32 s0, s0, 0x100
	s_addc_u32 s1, s1, 0
	s_cmp_gt_u32 s51, 13
	s_cbranch_scc0 .LBB0_378
	s_and_b64 vcc, exec, s[16:17]
	s_cbranch_vccz .LBB0_381
	s_barrier

; #define PG8_STAGE(bufoff, gbase, voff) do { _Pragma("unroll") for (int _i = 0; _i < 2; ++_i) \
;         __builtin_amdgcn_global_load_lds((const unsigned*)((const char*)(gbase) + (voff)[_i]), (PG8_LAS unsigned*)(lds + (bufoff) + ldsw + _i * 8192), 16, 0, 0); } while (0)
; #define PG8_WAIT_V(n) asm volatile("s_waitcnt vmcnt(" #n ")" ::: "memory")
; #define PG8_BAR __builtin_amdgcn_s_barrier()
; template <class Epi, class Sched, bool ALIGN_EPI = false, bool SP2 = false>
; __device__ __forceinline__ void gemm_phase(PG8_LAS unsigned char* lds, const Gemm g, const Sched& S, const Epi& E) {
;     ...
;     const int tid = tid_, wid = __builtin_amdgcn_readfirstlane(tid >> 6), lane = tid & 63, wr = wid >> 2, wc = wid & 3, fr = lane & 15, fq = lane >> 4;
;     const int K = g.K, nt = K / BK;
;     unsigned voffA[2], voffB[2];
; #pragma unroll
;     for (int i = 0; i < 2; ++i) { int R, C; stage_rc(tid * 16 + i * 8192, R, C); const int Rb = Epi::PERM ? ((R & ~31) + perm32(R & 31)) : R;
;         voffA[i] = (unsigned)(R * K + C) * 2u; voffB[i] = (unsigned)(Rb * K + C) * 2u; }
;     const size_t kstep = (size_t)(BK * 2);
;     const size_t hstep = (size_t)HALF * K * 2;
;     const size_t tstep = 2 * hstep;
;     const unsigned ldsw = (unsigned)wid * 1024u;
;     const int aoff = lds_byte(wr * 64 + fr, fq * 8), boff = lds_byte(wc * 32 + fr, fq * 8);
;     ...
;         PG8_STAGE(PG8_SB(1, 0), cB + kstep, voffB); PG8_STAGE(PG8_SA(1, 0), cA + kstep, voffA); PG8_STAGE(PG8_SB(1, 1), cB + hstep + kstep, voffB);
;         PG8_WAIT_V(6); PG8_BAR;
.LBB0_436:
	v_readlane_b32 s4, v254, 33
	v_readlane_b32 s5, v254, 34
	v_readlane_b32 s36, v253, 12
	v_bfe_u32 v18, v16, 4, 2
	s_and_b64 s[4:5], s[4:5], exec
	v_readlane_b32 s37, v253, 13
	v_and_b32_e32 v17, 15, v16
	v_lshlrev_b32_e32 v19, 4, v18
	v_lshlrev_b32_e32 v16, 2, v16
	s_cselect_b32 s5, s37, s11
	s_cselect_b32 s4, s36, s10
	s_and_b32 s8, s6, 3
	v_lshl_or_b32 v140, s1, 6, v17
	v_lshl_or_b32 v17, v17, 6, v19
	s_lshl_b32 s1, s1, 13
	v_and_b32_e32 v16, 32, v16
	s_add_i32 m0, s31, 0x18000
	v_lshl_add_u64 v[8:9], v[8:9], 0, s[96:97]
	v_bitop3_b32 v19, v17, s1, v16 bitop3:0xde
	s_lshl_b32 s1, s8, 12
	s_waitcnt vmcnt(2)
	s_barrier
	global_load_lds_dwordx4 v[8:9], off
	v_lshl_add_u64 v[6:7], v[6:7], 0, s[96:97]
	s_add_i32 m0, s31, 0x1a000
	s_add_i32 s36, s31, 0x8000
	s_add_i32 s37, s31, 0xa000
	global_load_lds_dwordx4 v[6:7], off
	v_lshl_add_u64 v[2:3], v[2:3], 0, s[96:97]
	s_mov_b32 m0, s36
	s_add_u32 s6, s18, 0x40080
	global_load_lds_dwordx4 v[2:3], off
	v_lshl_add_u64 v[2:3], v[4:5], 0, s[96:97]
	s_mov_b32 m0, s37
	s_addc_u32 s7, s19, 0
	global_load_lds_dwordx4 v[2:3], off
	s_add_i32 m0, s31, 0x1c000
	v_lshl_add_u64 v[2:3], s[6:7], 0, v[0:1]
	global_load_lds_dwordx4 v[2:3], off
	v_lshl_add_u64 v[2:3], s[6:7], 0, v[130:131]
	s_add_i32 m0, s31, 0x1e000
	v_readlane_b32 s38, v253, 14
	global_load_lds_dwordx4 v[2:3], off
	v_lshlrev_b32_e32 v2, 2, v18
	v_lshl_or_b32 v142, s8, 5, v2
	v_lshlrev_b32_e32 v2, 14, v10
	v_and_b32_e32 v2, 0xffff8000, v2
	v_lshl_add_u32 v2, v11, 11, v2
	v_and_b32_e32 v3, 1, v10
	v_lshl_or_b32 v2, v3, 6, v2
	v_lshl_add_u32 v132, v12, 1, v2
	v_lshlrev_b32_e32 v2, 14, v13
	v_and_b32_e32 v2, 0xffff8000, v2
	s_waitcnt vmcnt(6)
	v_lshl_add_u32 v2, v14, 11, v2
	v_and_b32_e32 v3, 1, v13
	v_readlane_b32 s39, v253, 15
	v_readlane_b32 s40, v253, 16
	v_readlane_b32 s41, v253, 17
	v_bitop3_b32 v141, v17, s1, v16 bitop3:0xde
	s_cmpk_lt_u32 s0, 0x100
	v_lshl_or_b32 v2, v3, 6, v2
	v_readlane_b32 s0, v254, 1
	s_cselect_b64 s[6:7], -1, 0
	s_waitcnt lgkmcnt(0)
	s_ashr_i32 s38, s30, 31
	v_mov_b32_e32 v133, v1
	v_lshl_add_u32 v134, v15, 1, v2
	v_mov_b32_e32 v135, v1
	s_mov_b32 s39, 0
	v_add_u32_e32 v143, 0, v19
	v_readlane_b32 s40, v254, 0
	s_mov_b32 s41, s0
	v_readlane_b32 s42, v253, 18
	v_readlane_b32 s43, v253, 19
	v_readlane_b32 s44, v253, 20
	v_readlane_b32 s45, v253, 21
	v_readlane_b32 s46, v253, 22
	v_readlane_b32 s47, v253, 23
	v_readlane_b32 s48, v253, 24
	v_readlane_b32 s49, v253, 25
	v_readlane_b32 s50, v253, 26
	v_readlane_b32 s51, v253, 27
	s_barrier
	v_readlane_b32 s1, v254, 2
	v_readfirstlane_b32 s100, v210
	s_nop 3
	s_lshr_b32 s100, s100, 6
	s_cmp_lt_u32 s100, 4
	s_cbranch_scc1 .Lgp_g3
	s_setprio 1

; #define PG8_STAGE(bufoff, gbase, voff) do { _Pragma("unroll") for (int _i = 0; _i < 2; ++_i) \
;         __builtin_amdgcn_global_load_lds((const unsigned*)((const char*)(gbase) + (voff)[_i]), (PG8_LAS unsigned*)(lds + (bufoff) + ldsw + _i * 8192), 16, 0, 0); } while (0)
; #define PG8_LDA(dst, b, h) do { _Pragma("unroll") for (int m = 0; m < 4; ++m) _Pragma("unroll") for (int k = 0; k < 2; ++k) dst[m][k] = *(const PG8_LAS bf16x8*)(lds + PG8_SA(b, h) + aoff + m * 2048 + k * 1024); } while (0)
; #define PG8_LDB(dst, b, h) do { _Pragma("unroll") for (int n = 0; n < 2; ++n) _Pragma("unroll") for (int k = 0; k < 2; ++k) dst[n][k] = *(const PG8_LAS bf16x8*)(lds + PG8_SB(b, h) + boff + n * 2048 + k * 1024); } while (0)
; #define PG8_MMA(ai, bj, At, Bt) do { __builtin_amdgcn_s_setprio(1); _Pragma("unroll") for (int m = 0; m < 4; ++m) _Pragma("unroll") for (int n = 0; n < 2; ++n) _Pragma("unroll") for (int k = 0; k < 2; ++k) \
;         acc[ai][bj][m][n] = __builtin_amdgcn_mfma_f32_16x16x32_bf16(Bt[n][k], At[m][k], acc[ai][bj][m][n], 0, 0, 0); __builtin_amdgcn_s_setprio(0); } while (0)
; #define PG8_WAIT_V(n) asm volatile("s_waitcnt vmcnt(" #n ")" ::: "memory")
; #define PG8_WAIT_L(n) asm volatile("s_waitcnt lgkmcnt(" #n ")" ::: "memory")
; #define PG8_BAR __builtin_amdgcn_s_barrier()
; #define PG8_SCHED __builtin_amdgcn_sched_barrier(0)
; template <class Epi, class Sched, bool ALIGN_EPI = false, bool SP2 = false>
; __device__ __forceinline__ void gemm_phase(PG8_LAS unsigned char* lds, const Gemm g, const Sched& S, const Epi& E) {
;     ...
;             PG8_LDB(B0, 0, 0); PG8_LDB(B1, 0, 1); PG8_SCHED; PG8_LDA(At, 0, 0); PG8_STAGE(PG8_SA(1, 1), a1 + hstep, voffA);
;             PG8_WAIT_V(8); PG8_WAIT_L(0); PG8_BAR; PG8_MMA(0, 0, At, B0); PG8_MMA(0, 1, At, B1); PG8_BAR; PG8_SCHED;
;             PG8_LDA(At, 0, 1); PG8_STAGE(PG8_SB(0, 0), b2, voffB); PG8_STAGE(PG8_SB(0, 1), b2 + hstep, voffB); PG8_STAGE(PG8_SA(0, 0), a2, voffA);
;             PG8_WAIT_V(8); PG8_WAIT_L(0); PG8_BAR; PG8_MMA(1, 0, At, B0); PG8_MMA(1, 1, At, B1); PG8_BAR; PG8_SCHED;
.LBB0_446:
	s_add_u32 s22, s18, 0xfffc0080
	s_addc_u32 s23, s19, -1
	s_add_i32 s47, 0, 0x10000
	s_cmp_eq_u32 s46, 12
	s_cselect_b32 s25, s13, s23
	s_cselect_b32 s24, s42, s22
	s_cselect_b32 s23, s9, s45
	s_cselect_b32 s22, s43, s44
	s_add_i32 s50, 0, 0x14000
	v_add_u32_e32 v152, s47, v141
	v_add_u32_e32 v168, s50, v141
	ds_read_b128 v[136:139], v152
	ds_read_b128 v[144:147], v152 offset:1024
	ds_read_b128 v[148:151], v152 offset:2048
	ds_read_b128 v[152:155], v152 offset:3072
	ds_read_b128 v[156:159], v168
	ds_read_b128 v[160:163], v168 offset:1024
	ds_read_b128 v[164:167], v168 offset:2048
	ds_read_b128 v[168:171], v168 offset:3072
	v_lshl_add_u64 v[192:193], s[18:19], 0, v[134:135]
	s_add_i32 m0, s31, 0xc000
	ds_read_b128 v[172:175], v143
	ds_read_b128 v[176:179], v143 offset:1024
	ds_read_b128 v[180:183], v143 offset:2048
	ds_read_b128 v[184:187], v143 offset:3072
	ds_read_b128 v[188:191], v143 offset:4096
	ds_read_b128 v[206:209], v143 offset:5120
	ds_read_b128 v[222:225], v143 offset:6144
	ds_read_b128 v[226:229], v143 offset:7168
	global_load_lds_dwordx4 v[192:193], off
	v_lshl_add_u64 v[192:193], s[18:19], 0, v[132:133]
	s_add_i32 m0, s31, 0xe000
	s_nop 0
	global_load_lds_dwordx4 v[192:193], off
	s_waitcnt vmcnt(8)
	s_waitcnt lgkmcnt(0)
	s_barrier
	s_nop 0
	s_waitcnt lgkmcnt(0)
	v_mfma_f32_16x16x32_bf16 v[126:129], v[136:139], v[172:175], v[126:129]
	v_mfma_f32_16x16x32_bf16 v[122:125], v[148:151], v[172:175], v[122:125]
	v_mfma_f32_16x16x32_bf16 v[114:117], v[136:139], v[180:183], v[114:117]
	v_mfma_f32_16x16x32_bf16 v[110:113], v[148:151], v[180:183], v[110:113]
	v_mfma_f32_16x16x32_bf16 v[98:101], v[136:139], v[188:191], v[98:101]
	v_mfma_f32_16x16x32_bf16 v[94:97], v[148:151], v[188:191], v[94:97]
	v_mfma_f32_16x16x32_bf16 v[82:85], v[136:139], v[222:225], v[82:85]
	v_mfma_f32_16x16x32_bf16 v[78:81], v[148:151], v[222:225], v[78:81]
	v_mfma_f32_16x16x32_bf16 v[126:129], v[144:147], v[176:179], v[126:129]
	v_mfma_f32_16x16x32_bf16 v[122:125], v[152:155], v[176:179], v[122:125]
	v_mfma_f32_16x16x32_bf16 v[114:117], v[144:147], v[184:187], v[114:117]
	v_mfma_f32_16x16x32_bf16 v[110:113], v[152:155], v[184:187], v[110:113]
	v_mfma_f32_16x16x32_bf16 v[98:101], v[144:147], v[206:209], v[98:101]
	v_mfma_f32_16x16x32_bf16 v[94:97], v[152:155], v[206:209], v[94:97]
	v_mfma_f32_16x16x32_bf16 v[82:85], v[144:147], v[226:229], v[82:85]
	v_mfma_f32_16x16x32_bf16 v[78:81], v[152:155], v[226:229], v[78:81]
	s_nop 0
	s_nop 0
	v_mfma_f32_16x16x32_bf16 v[118:121], v[156:159], v[172:175], v[118:121]
	v_mfma_f32_16x16x32_bf16 v[106:109], v[164:167], v[172:175], v[106:109]
	v_mfma_f32_16x16x32_bf16 v[102:105], v[156:159], v[180:183], v[102:105]
	v_mfma_f32_16x16x32_bf16 v[90:93], v[164:167], v[180:183], v[90:93]
	v_mfma_f32_16x16x32_bf16 v[86:89], v[156:159], v[188:191], v[86:89]
	v_mfma_f32_16x16x32_bf16 v[74:77], v[164:167], v[188:191], v[74:77]
	v_mfma_f32_16x16x32_bf16 v[70:73], v[156:159], v[222:225], v[70:73]
	v_mfma_f32_16x16x32_bf16 v[66:69], v[164:167], v[222:225], v[66:69]
	v_mfma_f32_16x16x32_bf16 v[118:121], v[160:163], v[176:179], v[118:121]
	v_mfma_f32_16x16x32_bf16 v[106:109], v[168:171], v[176:179], v[106:109]
	v_mfma_f32_16x16x32_bf16 v[102:105], v[160:163], v[184:187], v[102:105]
	v_mfma_f32_16x16x32_bf16 v[90:93], v[168:171], v[184:187], v[90:93]
	v_mfma_f32_16x16x32_bf16 v[86:89], v[160:163], v[206:209], v[86:89]
	v_mfma_f32_16x16x32_bf16 v[74:77], v[168:171], v[206:209], v[74:77]
	v_mfma_f32_16x16x32_bf16 v[70:73], v[160:163], v[226:229], v[70:73]
	v_mfma_f32_16x16x32_bf16 v[66:69], v[168:171], v[226:229], v[66:69]
	s_nop 0
	s_barrier
	s_add_i32 s47, s47, s27
	v_lshl_add_u64 v[192:193], s[22:23], 0, v[0:1]
	s_mov_b32 m0, s47
	ds_read_b128 v[172:175], v143 offset:16384
	ds_read_b128 v[176:179], v143 offset:17408
	ds_read_b128 v[180:183], v143 offset:18432
	ds_read_b128 v[184:187], v143 offset:19456
	ds_read_b128 v[188:191], v143 offset:20480
	ds_read_b128 v[206:209], v143 offset:21504
	ds_read_b128 v[222:225], v143 offset:22528
	ds_read_b128 v[226:229], v143 offset:23552
	global_load_lds_dwordx4 v[192:193], off
	s_add_i32 m0, s47, 0x2000
	s_add_u32 s48, s22, 0x40000
	v_lshl_add_u64 v[230:231], s[22:23], 0, v[130:131]
	s_addc_u32 s49, s23, 0
	s_add_i32 s47, s50, s27
	global_load_lds_dwordx4 v[230:231], off
	v_lshl_add_u64 v[232:233], s[48:49], 0, v[0:1]
	s_mov_b32 m0, s47
	v_lshl_add_u64 v[234:235], s[24:25], 0, v[130:131]
	global_load_lds_dwordx4 v[232:233], off
	v_lshl_add_u64 v[232:233], s[48:49], 0, v[130:131]
	s_add_i32 m0, s47, 0x2000
	s_nop 0
	global_load_lds_dwordx4 v[232:233], off
	v_lshl_add_u64 v[232:233], s[24:25], 0, v[0:1]
	s_mov_b32 m0, s31
	s_nop 0
	global_load_lds_dwordx4 v[232:233], off
	s_mov_b32 m0, s33
	s_nop 0
	global_load_lds_dwordx4 v[234:235], off
	s_waitcnt vmcnt(8)
	s_waitcnt lgkmcnt(0)
	s_barrier
; #define PG8_STAGE(bufoff, gbase, voff) do { _Pragma("unroll") for (int _i = 0; _i < 2; ++_i) \
;         __builtin_amdgcn_global_load_lds((const unsigned*)((const char*)(gbase) + (voff)[_i]), (PG8_LAS unsigned*)(lds + (bufoff) + ldsw + _i * 8192), 16, 0, 0); } while (0)
; #define PG8_LDA(dst, b, h) do { _Pragma("unroll") for (int m = 0; m < 4; ++m) _Pragma("unroll") for (int k = 0; k < 2; ++k) dst[m][k] = *(const PG8_LAS bf16x8*)(lds + PG8_SA(b, h) + aoff + m * 2048 + k * 1024); } while (0)
; #define PG8_LDB(dst, b, h) do { _Pragma("unroll") for (int n = 0; n < 2; ++n) _Pragma("unroll") for (int k = 0; k < 2; ++k) dst[n][k] = *(const PG8_LAS bf16x8*)(lds + PG8_SB(b, h) + boff + n * 2048 + k * 1024); } while (0)
; #define PG8_MMA(ai, bj, At, Bt) do { __builtin_amdgcn_s_setprio(1); _Pragma("unroll") for (int m = 0; m < 4; ++m) _Pragma("unroll") for (int n = 0; n < 2; ++n) _Pragma("unroll") for (int k = 0; k < 2; ++k) \
;         acc[ai][bj][m][n] = __builtin_amdgcn_mfma_f32_16x16x32_bf16(Bt[n][k], At[m][k], acc[ai][bj][m][n], 0, 0, 0); __builtin_amdgcn_s_setprio(0); } while (0)
; #define PG8_WAIT_V(n) asm volatile("s_waitcnt vmcnt(" #n ")" ::: "memory")
; #define PG8_WAIT_L(n) asm volatile("s_waitcnt lgkmcnt(" #n ")" ::: "memory")
; #define PG8_BAR __builtin_amdgcn_s_barrier()
; #define PG8_SCHED __builtin_amdgcn_sched_barrier(0)
; template <class Epi, class Sched, bool ALIGN_EPI = false, bool SP2 = false>
; __device__ __forceinline__ void gemm_phase(PG8_LAS unsigned char* lds, const Gemm g, const Sched& S, const Epi& E) {
;     ...
;             PG8_WAIT_V(8); PG8_WAIT_L(0); PG8_BAR; PG8_MMA(1, 0, At, B0); PG8_MMA(1, 1, At, B1); PG8_BAR; PG8_SCHED;
;             PG8_LDB(B0, 1, 0); PG8_LDB(B1, 1, 1); PG8_SCHED; PG8_LDA(At, 1, 0); PG8_STAGE(PG8_SA(0, 1), a2 + hstep, voffA);
;             PG8_WAIT_V(8); PG8_WAIT_L(0); PG8_BAR; PG8_MMA(0, 0, At, B0); PG8_MMA(0, 1, At, B1); PG8_BAR; PG8_SCHED;
	s_nop 0
	s_waitcnt lgkmcnt(0)
	v_mfma_f32_16x16x32_bf16 v[62:65], v[136:139], v[172:175], v[62:65]
	v_mfma_f32_16x16x32_bf16 v[58:61], v[148:151], v[172:175], v[58:61]
	v_mfma_f32_16x16x32_bf16 v[50:53], v[136:139], v[180:183], v[50:53]
	v_mfma_f32_16x16x32_bf16 v[46:49], v[148:151], v[180:183], v[46:49]
	v_mfma_f32_16x16x32_bf16 v[34:37], v[136:139], v[188:191], v[34:37]
	v_mfma_f32_16x16x32_bf16 v[30:33], v[148:151], v[188:191], v[30:33]
	v_mfma_f32_16x16x32_bf16 v[18:21], v[136:139], v[222:225], v[18:21]
	v_mfma_f32_16x16x32_bf16 v[14:17], v[148:151], v[222:225], v[14:17]
	v_mfma_f32_16x16x32_bf16 v[62:65], v[144:147], v[176:179], v[62:65]
	v_mfma_f32_16x16x32_bf16 v[58:61], v[152:155], v[176:179], v[58:61]
	v_mfma_f32_16x16x32_bf16 v[50:53], v[144:147], v[184:187], v[50:53]
	v_mfma_f32_16x16x32_bf16 v[46:49], v[152:155], v[184:187], v[46:49]
	v_mfma_f32_16x16x32_bf16 v[34:37], v[144:147], v[206:209], v[34:37]
	v_mfma_f32_16x16x32_bf16 v[30:33], v[152:155], v[206:209], v[30:33]
	v_mfma_f32_16x16x32_bf16 v[18:21], v[144:147], v[226:229], v[18:21]
	v_mfma_f32_16x16x32_bf16 v[14:17], v[152:155], v[226:229], v[14:17]
	s_nop 0
	s_nop 0
	v_mfma_f32_16x16x32_bf16 v[54:57], v[156:159], v[172:175], v[54:57]
	v_mfma_f32_16x16x32_bf16 v[42:45], v[164:167], v[172:175], v[42:45]
	v_mfma_f32_16x16x32_bf16 v[38:41], v[156:159], v[180:183], v[38:41]
	v_mfma_f32_16x16x32_bf16 v[26:29], v[164:167], v[180:183], v[26:29]
	v_mfma_f32_16x16x32_bf16 v[22:25], v[156:159], v[188:191], v[22:25]
	v_mfma_f32_16x16x32_bf16 v[10:13], v[164:167], v[188:191], v[10:13]
	v_mfma_f32_16x16x32_bf16 v[6:9], v[156:159], v[222:225], v[6:9]
	v_mfma_f32_16x16x32_bf16 v[2:5], v[164:167], v[222:225], v[2:5]
	v_mfma_f32_16x16x32_bf16 v[54:57], v[160:163], v[176:179], v[54:57]
	v_mfma_f32_16x16x32_bf16 v[42:45], v[168:171], v[176:179], v[42:45]
	v_mfma_f32_16x16x32_bf16 v[38:41], v[160:163], v[184:187], v[38:41]
	v_mfma_f32_16x16x32_bf16 v[26:29], v[168:171], v[184:187], v[26:29]
	v_mfma_f32_16x16x32_bf16 v[22:25], v[160:163], v[206:209], v[22:25]
	v_mfma_f32_16x16x32_bf16 v[10:13], v[168:171], v[206:209], v[10:13]
	v_mfma_f32_16x16x32_bf16 v[6:9], v[160:163], v[226:229], v[6:9]
	v_mfma_f32_16x16x32_bf16 v[2:5], v[168:171], v[226:229], v[2:5]
	s_nop 0
	s_barrier
	s_add_i32 s47, 0, 0x18000
	s_add_i32 s48, 0, 0x1c000
	v_add_u32_e32 v152, s47, v141
	v_add_u32_e32 v168, s48, v141
	ds_read_b128 v[136:139], v152
	ds_read_b128 v[144:147], v152 offset:1024
	ds_read_b128 v[148:151], v152 offset:2048
	ds_read_b128 v[152:155], v152 offset:3072
	ds_read_b128 v[156:159], v168
	ds_read_b128 v[160:163], v168 offset:1024
	ds_read_b128 v[164:167], v168 offset:2048
	ds_read_b128 v[168:171], v168 offset:3072
	s_add_u32 s24, s24, 0x40000
	s_addc_u32 s25, s25, 0
	s_mov_b32 m0, s34
	v_lshl_add_u64 v[236:237], s[24:25], 0, v[0:1]
	ds_read_b128 v[172:175], v143 offset:32768
	ds_read_b128 v[176:179], v143 offset:33792
	ds_read_b128 v[180:183], v143 offset:34816
	ds_read_b128 v[184:187], v143 offset:35840
	ds_read_b128 v[188:191], v143 offset:36864
	ds_read_b128 v[206:209], v143 offset:37888
	ds_read_b128 v[222:225], v143 offset:38912
	ds_read_b128 v[226:229], v143 offset:39936
	global_load_lds_dwordx4 v[236:237], off
	v_lshl_add_u64 v[236:237], s[24:25], 0, v[130:131]
	s_mov_b32 m0, s35
	s_nop 0
	global_load_lds_dwordx4 v[236:237], off
	s_waitcnt vmcnt(8)
	s_waitcnt lgkmcnt(0)
	s_barrier
	s_nop 0
	s_waitcnt lgkmcnt(0)
	v_mfma_f32_16x16x32_bf16 v[126:129], v[136:139], v[172:175], v[126:129]
	v_mfma_f32_16x16x32_bf16 v[122:125], v[148:151], v[172:175], v[122:125]
	v_mfma_f32_16x16x32_bf16 v[114:117], v[136:139], v[180:183], v[114:117]
	v_mfma_f32_16x16x32_bf16 v[110:113], v[148:151], v[180:183], v[110:113]
	v_mfma_f32_16x16x32_bf16 v[98:101], v[136:139], v[188:191], v[98:101]
	v_mfma_f32_16x16x32_bf16 v[94:97], v[148:151], v[188:191], v[94:97]
	v_mfma_f32_16x16x32_bf16 v[82:85], v[136:139], v[222:225], v[82:85]
	v_mfma_f32_16x16x32_bf16 v[78:81], v[148:151], v[222:225], v[78:81]
	v_mfma_f32_16x16x32_bf16 v[126:129], v[144:147], v[176:179], v[126:129]
	v_mfma_f32_16x16x32_bf16 v[122:125], v[152:155], v[176:179], v[122:125]
	v_mfma_f32_16x16x32_bf16 v[114:117], v[144:147], v[184:187], v[114:117]
	v_mfma_f32_16x16x32_bf16 v[110:113], v[152:155], v[184:187], v[110:113]
	v_mfma_f32_16x16x32_bf16 v[98:101], v[144:147], v[206:209], v[98:101]
	v_mfma_f32_16x16x32_bf16 v[94:97], v[152:155], v[206:209], v[94:97]
	v_mfma_f32_16x16x32_bf16 v[82:85], v[144:147], v[226:229], v[82:85]
	v_mfma_f32_16x16x32_bf16 v[78:81], v[152:155], v[226:229], v[78:81]
	s_nop 0
	s_nop 0
	v_mfma_f32_16x16x32_bf16 v[118:121], v[156:159], v[172:175], v[118:121]
	v_mfma_f32_16x16x32_bf16 v[106:109], v[164:167], v[172:175], v[106:109]
	v_mfma_f32_16x16x32_bf16 v[102:105], v[156:159], v[180:183], v[102:105]
	v_mfma_f32_16x16x32_bf16 v[90:93], v[164:167], v[180:183], v[90:93]
	v_mfma_f32_16x16x32_bf16 v[86:89], v[156:159], v[188:191], v[86:89]
	v_mfma_f32_16x16x32_bf16 v[74:77], v[164:167], v[188:191], v[74:77]
	v_mfma_f32_16x16x32_bf16 v[70:73], v[156:159], v[222:225], v[70:73]
	v_mfma_f32_16x16x32_bf16 v[66:69], v[164:167], v[222:225], v[66:69]
	v_mfma_f32_16x16x32_bf16 v[118:121], v[160:163], v[176:179], v[118:121]
	v_mfma_f32_16x16x32_bf16 v[106:109], v[168:171], v[176:179], v[106:109]
	v_mfma_f32_16x16x32_bf16 v[102:105], v[160:163], v[184:187], v[102:105]
	v_mfma_f32_16x16x32_bf16 v[90:93], v[168:171], v[184:187], v[90:93]
	v_mfma_f32_16x16x32_bf16 v[86:89], v[160:163], v[206:209], v[86:89]
	v_mfma_f32_16x16x32_bf16 v[74:77], v[168:171], v[206:209], v[74:77]
	v_mfma_f32_16x16x32_bf16 v[70:73], v[160:163], v[226:229], v[70:73]
	v_mfma_f32_16x16x32_bf16 v[66:69], v[168:171], v[226:229], v[66:69]
	s_nop 0
	s_barrier
; #define PG8_STAGE(bufoff, gbase, voff) do { _Pragma("unroll") for (int _i = 0; _i < 2; ++_i) \
;         __builtin_amdgcn_global_load_lds((const unsigned*)((const char*)(gbase) + (voff)[_i]), (PG8_LAS unsigned*)(lds + (bufoff) + ldsw + _i * 8192), 16, 0, 0); } while (0)
; #define PG8_LDA(dst, b, h) do { _Pragma("unroll") for (int m = 0; m < 4; ++m) _Pragma("unroll") for (int k = 0; k < 2; ++k) dst[m][k] = *(const PG8_LAS bf16x8*)(lds + PG8_SA(b, h) + aoff + m * 2048 + k * 1024); } while (0)
; #define PG8_MMA(ai, bj, At, Bt) do { __builtin_amdgcn_s_setprio(1); _Pragma("unroll") for (int m = 0; m < 4; ++m) _Pragma("unroll") for (int n = 0; n < 2; ++n) _Pragma("unroll") for (int k = 0; k < 2; ++k) \
;         acc[ai][bj][m][n] = __builtin_amdgcn_mfma_f32_16x16x32_bf16(Bt[n][k], At[m][k], acc[ai][bj][m][n], 0, 0, 0); __builtin_amdgcn_s_setprio(0); } while (0)
; #define PG8_WAIT_V(n) asm volatile("s_waitcnt vmcnt(" #n ")" ::: "memory")
; #define PG8_WAIT_L(n) asm volatile("s_waitcnt lgkmcnt(" #n ")" ::: "memory")
; #define PG8_BAR __builtin_amdgcn_s_barrier()
; #define PG8_SCHED __builtin_amdgcn_sched_barrier(0)
; template <class Epi, class Sched, bool ALIGN_EPI = false, bool SP2 = false>
; __device__ __forceinline__ void gemm_phase(PG8_LAS unsigned char* lds, const Gemm g, const Sched& S, const Epi& E) {
;     ...
;         for (int t = 0; t < nt; t += 2) {
;             const bool last = (t == nt - 2);
;     ...
;             PG8_LDA(At, 1, 1); PG8_STAGE(PG8_SB(1, 0), b3, voffB); PG8_STAGE(PG8_SB(1, 1), b3 + hstep, voffB); PG8_STAGE(PG8_SA(1, 0), a3, voffA);
;             PG8_WAIT_V(8); PG8_WAIT_L(0); PG8_BAR; PG8_MMA(1, 0, At, B0); PG8_MMA(1, 1, At, B1); PG8_BAR; PG8_SCHED;
	s_add_i32 s24, s47, s27
	v_lshl_add_u64 v[192:193], v[192:193], 0, s[96:97]
	s_mov_b32 m0, s24
	ds_read_b128 v[172:175], v143 offset:49152
	ds_read_b128 v[176:179], v143 offset:50176
	ds_read_b128 v[180:183], v143 offset:51200
	ds_read_b128 v[184:187], v143 offset:52224
	ds_read_b128 v[188:191], v143 offset:53248
	ds_read_b128 v[206:209], v143 offset:54272
	ds_read_b128 v[222:225], v143 offset:55296
	ds_read_b128 v[226:229], v143 offset:56320
	global_load_lds_dwordx4 v[192:193], off
	s_add_i32 m0, s24, 0x2000
	s_add_u32 s22, s22, 0x40080
	v_lshl_add_u64 v[192:193], v[230:231], 0, s[96:97]
	s_addc_u32 s23, s23, 0
	s_add_i32 s24, s48, s27
	global_load_lds_dwordx4 v[192:193], off
	v_lshl_add_u64 v[192:193], s[22:23], 0, v[0:1]
	s_mov_b32 m0, s24
	s_nop 0
	global_load_lds_dwordx4 v[192:193], off
	v_lshl_add_u64 v[192:193], s[22:23], 0, v[130:131]
	s_add_i32 m0, s24, 0x2000
	s_nop 0
	global_load_lds_dwordx4 v[192:193], off
	v_lshl_add_u64 v[192:193], v[232:233], 0, s[96:97]
	s_mov_b32 m0, s36
	s_nop 0
	global_load_lds_dwordx4 v[192:193], off
	v_lshl_add_u64 v[192:193], v[234:235], 0, s[96:97]
	s_mov_b32 m0, s37
	s_nop 0
	global_load_lds_dwordx4 v[192:193], off
	s_waitcnt vmcnt(8)
	s_waitcnt lgkmcnt(0)
	s_barrier
	s_nop 0
	s_waitcnt lgkmcnt(0)
	v_mfma_f32_16x16x32_bf16 v[62:65], v[136:139], v[172:175], v[62:65]
	v_mfma_f32_16x16x32_bf16 v[58:61], v[148:151], v[172:175], v[58:61]
	v_mfma_f32_16x16x32_bf16 v[50:53], v[136:139], v[180:183], v[50:53]
	v_mfma_f32_16x16x32_bf16 v[46:49], v[148:151], v[180:183], v[46:49]
	v_mfma_f32_16x16x32_bf16 v[34:37], v[136:139], v[188:191], v[34:37]
	v_mfma_f32_16x16x32_bf16 v[30:33], v[148:151], v[188:191], v[30:33]
	v_mfma_f32_16x16x32_bf16 v[18:21], v[136:139], v[222:225], v[18:21]
	v_mfma_f32_16x16x32_bf16 v[14:17], v[148:151], v[222:225], v[14:17]
	v_mfma_f32_16x16x32_bf16 v[62:65], v[144:147], v[176:179], v[62:65]
	v_mfma_f32_16x16x32_bf16 v[58:61], v[152:155], v[176:179], v[58:61]
	v_mfma_f32_16x16x32_bf16 v[50:53], v[144:147], v[184:187], v[50:53]
	v_mfma_f32_16x16x32_bf16 v[46:49], v[152:155], v[184:187], v[46:49]
	v_mfma_f32_16x16x32_bf16 v[34:37], v[144:147], v[206:209], v[34:37]
	v_mfma_f32_16x16x32_bf16 v[30:33], v[152:155], v[206:209], v[30:33]
	v_mfma_f32_16x16x32_bf16 v[18:21], v[144:147], v[226:229], v[18:21]
	v_mfma_f32_16x16x32_bf16 v[14:17], v[152:155], v[226:229], v[14:17]
	s_nop 0
	s_nop 0
	v_mfma_f32_16x16x32_bf16 v[54:57], v[156:159], v[172:175], v[54:57]
	v_mfma_f32_16x16x32_bf16 v[42:45], v[164:167], v[172:175], v[42:45]
	v_mfma_f32_16x16x32_bf16 v[38:41], v[156:159], v[180:183], v[38:41]
	v_mfma_f32_16x16x32_bf16 v[26:29], v[164:167], v[180:183], v[26:29]
	v_mfma_f32_16x16x32_bf16 v[22:25], v[156:159], v[188:191], v[22:25]
	v_mfma_f32_16x16x32_bf16 v[10:13], v[164:167], v[188:191], v[10:13]
	v_mfma_f32_16x16x32_bf16 v[6:9], v[156:159], v[222:225], v[6:9]
	v_mfma_f32_16x16x32_bf16 v[2:5], v[164:167], v[222:225], v[2:5]
	v_mfma_f32_16x16x32_bf16 v[54:57], v[160:163], v[176:179], v[54:57]
	v_mfma_f32_16x16x32_bf16 v[42:45], v[168:171], v[176:179], v[42:45]
	v_mfma_f32_16x16x32_bf16 v[38:41], v[160:163], v[184:187], v[38:41]
	v_mfma_f32_16x16x32_bf16 v[26:29], v[168:171], v[184:187], v[26:29]
	v_mfma_f32_16x16x32_bf16 v[22:25], v[160:163], v[206:209], v[22:25]
	v_mfma_f32_16x16x32_bf16 v[10:13], v[168:171], v[206:209], v[10:13]
	v_mfma_f32_16x16x32_bf16 v[6:9], v[160:163], v[226:229], v[6:9]
	v_mfma_f32_16x16x32_bf16 v[2:5], v[168:171], v[226:229], v[2:5]
	s_nop 0
	s_barrier
	s_add_i32 s46, s46, 2
	s_add_u32 s44, s44, 0x100
	s_addc_u32 s45, s45, 0
	s_add_u32 s18, s18, 0x100
	s_addc_u32 s19, s19, 0
	s_cmp_gt_u32 s46, 13
	s_cbranch_scc0 .LBB0_446
	s_and_b64 vcc, exec, s[6:7]
	s_cbranch_vccz .LBB0_449
	s_barrier

; #define PG8_STAGE(bufoff, gbase, voff) do { _Pragma("unroll") for (int _i = 0; _i < 2; ++_i) \
;         __builtin_amdgcn_global_load_lds((const unsigned*)((const char*)(gbase) + (voff)[_i]), (PG8_LAS unsigned*)(lds + (bufoff) + ldsw + _i * 8192), 16, 0, 0); } while (0)
; #define PG8_WAIT_V(n) asm volatile("s_waitcnt vmcnt(" #n ")" ::: "memory")
; #define PG8_BAR __builtin_amdgcn_s_barrier()
; template <class Epi, class Sched, bool ALIGN_EPI = false, bool SP2 = false>
; __device__ __forceinline__ void gemm_phase(PG8_LAS unsigned char* lds, const Gemm g, const Sched& S, const Epi& E) {
;     ...
;     const int tid = tid_, wid = __builtin_amdgcn_readfirstlane(tid >> 6), lane = tid & 63, wr = wid >> 2, wc = wid & 3, fr = lane & 15, fq = lane >> 4;
;     const int K = g.K, nt = K / BK;
;     unsigned voffA[2], voffB[2];
; #pragma unroll
;     for (int i = 0; i < 2; ++i) { int R, C; stage_rc(tid * 16 + i * 8192, R, C); const int Rb = Epi::PERM ? ((R & ~31) + perm32(R & 31)) : R;
;         voffA[i] = (unsigned)(R * K + C) * 2u; voffB[i] = (unsigned)(Rb * K + C) * 2u; }
;     const size_t kstep = (size_t)(BK * 2);
;     const size_t hstep = (size_t)HALF * K * 2;
;     const size_t tstep = 2 * hstep;
;     const unsigned ldsw = (unsigned)wid * 1024u;
;     const int aoff = lds_byte(wr * 64 + fr, fq * 8), boff = lds_byte(wc * 32 + fr, fq * 8);
;     ...
;         PG8_STAGE(PG8_SB(1, 0), cB + kstep, voffB); PG8_STAGE(PG8_SA(1, 0), cA + kstep, voffA); PG8_STAGE(PG8_SB(1, 1), cB + hstep + kstep, voffB);
;         PG8_WAIT_V(6); PG8_BAR;
.LBB0_591:
	s_add_u32 s16, s0, 0x2a00000
	s_addc_u32 s17, s1, 0
	v_bfe_u32 v18, v16, 4, 2
	s_add_u32 s18, s0, 0x1b800000
	v_and_b32_e32 v17, 15, v16
	v_lshlrev_b32_e32 v19, 4, v18
	v_lshlrev_b32_e32 v16, 2, v16
	s_addc_u32 s19, s1, 0
	s_and_b32 s46, s20, 3
	v_lshl_or_b32 v144, s5, 6, v17
	v_lshl_or_b32 v17, v17, 6, v19
	s_lshl_b32 s0, s5, 13
	v_and_b32_e32 v16, 32, v16
	s_add_i32 m0, s41, 0x18000
	v_lshl_add_u64 v[8:9], v[8:9], 0, s[96:97]
	v_bitop3_b32 v19, v17, s0, v16 bitop3:0xde
	s_lshl_b32 s0, s46, 12
	s_waitcnt vmcnt(2)
	s_barrier
	global_load_lds_dwordx4 v[8:9], off
	v_lshl_add_u64 v[6:7], v[6:7], 0, s[96:97]
	s_add_i32 m0, s41, 0x1a000
	s_add_i32 s47, s41, 0x8000
	s_add_i32 s48, s41, 0xa000
	v_bitop3_b32 v145, v17, s0, v16 bitop3:0xde
	global_load_lds_dwordx4 v[6:7], off
	v_lshl_add_u64 v[2:3], v[2:3], 0, s[96:97]
	s_mov_b32 m0, s47
	s_add_u32 s0, s2, 0x40080
	global_load_lds_dwordx4 v[2:3], off
	v_lshl_add_u64 v[2:3], v[4:5], 0, s[96:97]
	s_mov_b32 m0, s48
	s_addc_u32 s1, s3, 0
	global_load_lds_dwordx4 v[2:3], off
	s_add_i32 m0, s41, 0x1c000
	v_lshl_add_u64 v[2:3], s[0:1], 0, v[0:1]
	global_load_lds_dwordx4 v[2:3], off
	v_lshl_add_u64 v[2:3], s[0:1], 0, v[130:131]
	s_add_i32 m0, s41, 0x1e000
	s_cmpk_lt_u32 s4, 0x100
	global_load_lds_dwordx4 v[2:3], off
	v_lshlrev_b32_e32 v2, 2, v18
	v_lshl_or_b32 v146, s46, 5, v2
	v_lshlrev_b32_e32 v2, 14, v10
	v_and_b32_e32 v2, 0xffff8000, v2
	v_lshl_add_u32 v2, v11, 11, v2
	v_and_b32_e32 v3, 1, v10
	v_lshl_or_b32 v2, v3, 6, v2
	v_lshl_add_u32 v132, v12, 1, v2
	v_lshlrev_b32_e32 v2, 14, v13
	v_and_b32_e32 v2, 0xffff8000, v2
	s_waitcnt vmcnt(6)
	v_lshl_add_u32 v2, v14, 11, v2
	v_and_b32_e32 v3, 1, v13
	v_lshl_or_b32 v2, v3, 6, v2
	v_readlane_b32 s4, v254, 1
	s_cselect_b64 s[22:23], -1, 0
	s_mov_b32 s49, 0
	v_cmp_eq_u32_e64 s[0:1], 0, v18
	s_waitcnt lgkmcnt(0)
	s_ashr_i32 s50, s45, 31
	v_mov_b32_e32 v133, v1
	v_lshl_add_u32 v134, v15, 1, v2
	v_mov_b32_e32 v135, v1
	v_add_u32_e32 v147, 0, v19
	v_readlane_b32 s20, v254, 0
	s_mov_b32 s33, s4
	s_barrier
	v_readlane_b32 s5, v254, 2
	v_readfirstlane_b32 s100, v210
	s_nop 3
	s_lshr_b32 s100, s100, 6
	s_cmp_lt_u32 s100, 4
	s_cbranch_scc1 .Lgp_g4
	s_setprio 1

; #define PG8_STAGE(bufoff, gbase, voff) do { _Pragma("unroll") for (int _i = 0; _i < 2; ++_i) \
;         __builtin_amdgcn_global_load_lds((const unsigned*)((const char*)(gbase) + (voff)[_i]), (PG8_LAS unsigned*)(lds + (bufoff) + ldsw + _i * 8192), 16, 0, 0); } while (0)
; #define PG8_LDA(dst, b, h) do { _Pragma("unroll") for (int m = 0; m < 4; ++m) _Pragma("unroll") for (int k = 0; k < 2; ++k) dst[m][k] = *(const PG8_LAS bf16x8*)(lds + PG8_SA(b, h) + aoff + m * 2048 + k * 1024); } while (0)
; #define PG8_LDB(dst, b, h) do { _Pragma("unroll") for (int n = 0; n < 2; ++n) _Pragma("unroll") for (int k = 0; k < 2; ++k) dst[n][k] = *(const PG8_LAS bf16x8*)(lds + PG8_SB(b, h) + boff + n * 2048 + k * 1024); } while (0)
; #define PG8_MMA(ai, bj, At, Bt) do { __builtin_amdgcn_s_setprio(1); _Pragma("unroll") for (int m = 0; m < 4; ++m) _Pragma("unroll") for (int n = 0; n < 2; ++n) _Pragma("unroll") for (int k = 0; k < 2; ++k) \
;         acc[ai][bj][m][n] = __builtin_amdgcn_mfma_f32_16x16x32_bf16(Bt[n][k], At[m][k], acc[ai][bj][m][n], 0, 0, 0); __builtin_amdgcn_s_setprio(0); } while (0)
; #define PG8_WAIT_V(n) asm volatile("s_waitcnt vmcnt(" #n ")" ::: "memory")
; #define PG8_WAIT_L(n) asm volatile("s_waitcnt lgkmcnt(" #n ")" ::: "memory")
; #define PG8_BAR __builtin_amdgcn_s_barrier()
; #define PG8_SCHED __builtin_amdgcn_sched_barrier(0)
; template <class Epi, class Sched, bool ALIGN_EPI = false, bool SP2 = false>
; __device__ __forceinline__ void gemm_phase(PG8_LAS unsigned char* lds, const Gemm g, const Sched& S, const Epi& E) {
;     ...
;             PG8_LDB(B0, 0, 0); PG8_LDB(B1, 0, 1); PG8_SCHED; PG8_LDA(At, 0, 0); PG8_STAGE(PG8_SA(1, 1), a1 + hstep, voffA);
;             PG8_WAIT_V(8); PG8_WAIT_L(0); PG8_BAR; PG8_MMA(0, 0, At, B0); PG8_MMA(0, 1, At, B1); PG8_BAR; PG8_SCHED;
;             PG8_LDA(At, 0, 1); PG8_STAGE(PG8_SB(0, 0), b2, voffB); PG8_STAGE(PG8_SB(0, 1), b2 + hstep, voffB); PG8_STAGE(PG8_SA(0, 0), a2, voffA);
;             PG8_WAIT_V(8); PG8_WAIT_L(0); PG8_BAR; PG8_MMA(1, 0, At, B0); PG8_MMA(1, 1, At, B1); PG8_BAR; PG8_SCHED;
.LBB0_601:
	s_add_u32 s6, s2, 0xfffc0080
	s_addc_u32 s7, s3, -1
	s_add_i32 s56, 0, 0x10000
	s_cmp_eq_u32 s55, 12
	s_cselect_b32 s35, s27, s7
	s_cselect_b32 s34, s51, s6
	s_cselect_b32 s7, s25, s54
	s_cselect_b32 s6, s52, s53
	s_add_i32 s58, 0, 0x14000
	v_add_u32_e32 v152, s56, v145
	v_add_u32_e32 v168, s58, v145
	ds_read_b128 v[136:139], v152
	ds_read_b128 v[140:143], v152 offset:1024
	ds_read_b128 v[148:151], v152 offset:2048
	ds_read_b128 v[152:155], v152 offset:3072
	ds_read_b128 v[156:159], v168
	ds_read_b128 v[160:163], v168 offset:1024
	ds_read_b128 v[164:167], v168 offset:2048
	ds_read_b128 v[168:171], v168 offset:3072
	v_lshl_add_u64 v[192:193], s[2:3], 0, v[134:135]
	s_add_i32 m0, s41, 0xc000
	ds_read_b128 v[172:175], v147
	ds_read_b128 v[176:179], v147 offset:1024
	ds_read_b128 v[180:183], v147 offset:2048
	ds_read_b128 v[184:187], v147 offset:3072
	ds_read_b128 v[188:191], v147 offset:4096
	ds_read_b128 v[206:209], v147 offset:5120
	ds_read_b128 v[222:225], v147 offset:6144
	ds_read_b128 v[226:229], v147 offset:7168
	global_load_lds_dwordx4 v[192:193], off
	v_lshl_add_u64 v[192:193], s[2:3], 0, v[132:133]
	s_add_i32 m0, s41, 0xe000
	s_nop 0
	global_load_lds_dwordx4 v[192:193], off
	s_waitcnt vmcnt(8)
	s_waitcnt lgkmcnt(0)
	s_barrier
	s_nop 0
	s_waitcnt lgkmcnt(0)
	v_mfma_f32_16x16x32_bf16 v[126:129], v[136:139], v[172:175], v[126:129]
	v_mfma_f32_16x16x32_bf16 v[122:125], v[148:151], v[172:175], v[122:125]
	v_mfma_f32_16x16x32_bf16 v[110:113], v[136:139], v[180:183], v[110:113]
	v_mfma_f32_16x16x32_bf16 v[106:109], v[148:151], v[180:183], v[106:109]
	v_mfma_f32_16x16x32_bf16 v[94:97], v[136:139], v[188:191], v[94:97]
	v_mfma_f32_16x16x32_bf16 v[90:93], v[148:151], v[188:191], v[90:93]
	v_mfma_f32_16x16x32_bf16 v[78:81], v[136:139], v[222:225], v[78:81]
	v_mfma_f32_16x16x32_bf16 v[74:77], v[148:151], v[222:225], v[74:77]
	v_mfma_f32_16x16x32_bf16 v[126:129], v[140:143], v[176:179], v[126:129]
	v_mfma_f32_16x16x32_bf16 v[122:125], v[152:155], v[176:179], v[122:125]
	v_mfma_f32_16x16x32_bf16 v[110:113], v[140:143], v[184:187], v[110:113]
	v_mfma_f32_16x16x32_bf16 v[106:109], v[152:155], v[184:187], v[106:109]
	v_mfma_f32_16x16x32_bf16 v[94:97], v[140:143], v[206:209], v[94:97]
	v_mfma_f32_16x16x32_bf16 v[90:93], v[152:155], v[206:209], v[90:93]
	v_mfma_f32_16x16x32_bf16 v[78:81], v[140:143], v[226:229], v[78:81]
	v_mfma_f32_16x16x32_bf16 v[74:77], v[152:155], v[226:229], v[74:77]
	s_nop 0
	s_nop 0
	v_mfma_f32_16x16x32_bf16 v[118:121], v[156:159], v[172:175], v[118:121]
	v_mfma_f32_16x16x32_bf16 v[114:117], v[164:167], v[172:175], v[114:117]
	v_mfma_f32_16x16x32_bf16 v[102:105], v[156:159], v[180:183], v[102:105]
	v_mfma_f32_16x16x32_bf16 v[98:101], v[164:167], v[180:183], v[98:101]
	v_mfma_f32_16x16x32_bf16 v[86:89], v[156:159], v[188:191], v[86:89]
	v_mfma_f32_16x16x32_bf16 v[82:85], v[164:167], v[188:191], v[82:85]
	v_mfma_f32_16x16x32_bf16 v[70:73], v[156:159], v[222:225], v[70:73]
	v_mfma_f32_16x16x32_bf16 v[66:69], v[164:167], v[222:225], v[66:69]
	v_mfma_f32_16x16x32_bf16 v[118:121], v[160:163], v[176:179], v[118:121]
	v_mfma_f32_16x16x32_bf16 v[114:117], v[168:171], v[176:179], v[114:117]
	v_mfma_f32_16x16x32_bf16 v[102:105], v[160:163], v[184:187], v[102:105]
	v_mfma_f32_16x16x32_bf16 v[98:101], v[168:171], v[184:187], v[98:101]
	v_mfma_f32_16x16x32_bf16 v[86:89], v[160:163], v[206:209], v[86:89]
	v_mfma_f32_16x16x32_bf16 v[82:85], v[168:171], v[206:209], v[82:85]
	v_mfma_f32_16x16x32_bf16 v[70:73], v[160:163], v[226:229], v[70:73]
	v_mfma_f32_16x16x32_bf16 v[66:69], v[168:171], v[226:229], v[66:69]
	s_nop 0
	s_barrier
	s_add_i32 s56, s56, s40
	v_lshl_add_u64 v[192:193], s[6:7], 0, v[0:1]
	s_mov_b32 m0, s56
	ds_read_b128 v[172:175], v147 offset:16384
	ds_read_b128 v[176:179], v147 offset:17408
	ds_read_b128 v[180:183], v147 offset:18432
	ds_read_b128 v[184:187], v147 offset:19456
	ds_read_b128 v[188:191], v147 offset:20480
	ds_read_b128 v[206:209], v147 offset:21504
	ds_read_b128 v[222:225], v147 offset:22528
	ds_read_b128 v[226:229], v147 offset:23552
	global_load_lds_dwordx4 v[192:193], off
	s_add_i32 m0, s56, 0x2000
	s_add_u32 s56, s6, 0x40000
	v_lshl_add_u64 v[230:231], s[6:7], 0, v[130:131]
	s_addc_u32 s57, s7, 0
	s_add_i32 s58, s58, s40
	global_load_lds_dwordx4 v[230:231], off
	v_lshl_add_u64 v[232:233], s[56:57], 0, v[0:1]
	s_mov_b32 m0, s58
	v_lshl_add_u64 v[234:235], s[34:35], 0, v[130:131]
	global_load_lds_dwordx4 v[232:233], off
	v_lshl_add_u64 v[232:233], s[56:57], 0, v[130:131]
	s_add_i32 m0, s58, 0x2000
	s_nop 0
	global_load_lds_dwordx4 v[232:233], off
	v_lshl_add_u64 v[232:233], s[34:35], 0, v[0:1]
	s_mov_b32 m0, s41
	s_nop 0
	global_load_lds_dwordx4 v[232:233], off
	s_mov_b32 m0, s42
	s_nop 0
	global_load_lds_dwordx4 v[234:235], off
	s_waitcnt vmcnt(8)
	s_waitcnt lgkmcnt(0)
	s_barrier
; #define PG8_STAGE(bufoff, gbase, voff) do { _Pragma("unroll") for (int _i = 0; _i < 2; ++_i) \
;         __builtin_amdgcn_global_load_lds((const unsigned*)((const char*)(gbase) + (voff)[_i]), (PG8_LAS unsigned*)(lds + (bufoff) + ldsw + _i * 8192), 16, 0, 0); } while (0)
; #define PG8_LDA(dst, b, h) do { _Pragma("unroll") for (int m = 0; m < 4; ++m) _Pragma("unroll") for (int k = 0; k < 2; ++k) dst[m][k] = *(const PG8_LAS bf16x8*)(lds + PG8_SA(b, h) + aoff + m * 2048 + k * 1024); } while (0)
; #define PG8_LDB(dst, b, h) do { _Pragma("unroll") for (int n = 0; n < 2; ++n) _Pragma("unroll") for (int k = 0; k < 2; ++k) dst[n][k] = *(const PG8_LAS bf16x8*)(lds + PG8_SB(b, h) + boff + n * 2048 + k * 1024); } while (0)
; #define PG8_MMA(ai, bj, At, Bt) do { __builtin_amdgcn_s_setprio(1); _Pragma("unroll") for (int m = 0; m < 4; ++m) _Pragma("unroll") for (int n = 0; n < 2; ++n) _Pragma("unroll") for (int k = 0; k < 2; ++k) \
;         acc[ai][bj][m][n] = __builtin_amdgcn_mfma_f32_16x16x32_bf16(Bt[n][k], At[m][k], acc[ai][bj][m][n], 0, 0, 0); __builtin_amdgcn_s_setprio(0); } while (0)
; #define PG8_WAIT_V(n) asm volatile("s_waitcnt vmcnt(" #n ")" ::: "memory")
; #define PG8_WAIT_L(n) asm volatile("s_waitcnt lgkmcnt(" #n ")" ::: "memory")
; #define PG8_BAR __builtin_amdgcn_s_barrier()
; #define PG8_SCHED __builtin_amdgcn_sched_barrier(0)
; template <class Epi, class Sched, bool ALIGN_EPI = false, bool SP2 = false>
; __device__ __forceinline__ void gemm_phase(PG8_LAS unsigned char* lds, const Gemm g, const Sched& S, const Epi& E) {
;     ...
;             PG8_WAIT_V(8); PG8_WAIT_L(0); PG8_BAR; PG8_MMA(1, 0, At, B0); PG8_MMA(1, 1, At, B1); PG8_BAR; PG8_SCHED;
;             PG8_LDB(B0, 1, 0); PG8_LDB(B1, 1, 1); PG8_SCHED; PG8_LDA(At, 1, 0); PG8_STAGE(PG8_SA(0, 1), a2 + hstep, voffA);
;             PG8_WAIT_V(8); PG8_WAIT_L(0); PG8_BAR; PG8_MMA(0, 0, At, B0); PG8_MMA(0, 1, At, B1); PG8_BAR; PG8_SCHED;
	s_nop 0
	s_waitcnt lgkmcnt(0)
	v_mfma_f32_16x16x32_bf16 v[62:65], v[136:139], v[172:175], v[62:65]
	v_mfma_f32_16x16x32_bf16 v[58:61], v[148:151], v[172:175], v[58:61]
	v_mfma_f32_16x16x32_bf16 v[46:49], v[136:139], v[180:183], v[46:49]
	v_mfma_f32_16x16x32_bf16 v[42:45], v[148:151], v[180:183], v[42:45]
	v_mfma_f32_16x16x32_bf16 v[30:33], v[136:139], v[188:191], v[30:33]
	v_mfma_f32_16x16x32_bf16 v[26:29], v[148:151], v[188:191], v[26:29]
	v_mfma_f32_16x16x32_bf16 v[14:17], v[136:139], v[222:225], v[14:17]
	v_mfma_f32_16x16x32_bf16 v[10:13], v[148:151], v[222:225], v[10:13]
	v_mfma_f32_16x16x32_bf16 v[62:65], v[140:143], v[176:179], v[62:65]
	v_mfma_f32_16x16x32_bf16 v[58:61], v[152:155], v[176:179], v[58:61]
	v_mfma_f32_16x16x32_bf16 v[46:49], v[140:143], v[184:187], v[46:49]
	v_mfma_f32_16x16x32_bf16 v[42:45], v[152:155], v[184:187], v[42:45]
	v_mfma_f32_16x16x32_bf16 v[30:33], v[140:143], v[206:209], v[30:33]
	v_mfma_f32_16x16x32_bf16 v[26:29], v[152:155], v[206:209], v[26:29]
	v_mfma_f32_16x16x32_bf16 v[14:17], v[140:143], v[226:229], v[14:17]
	v_mfma_f32_16x16x32_bf16 v[10:13], v[152:155], v[226:229], v[10:13]
	s_nop 0
	s_nop 0
	v_mfma_f32_16x16x32_bf16 v[54:57], v[156:159], v[172:175], v[54:57]
	v_mfma_f32_16x16x32_bf16 v[50:53], v[164:167], v[172:175], v[50:53]
	v_mfma_f32_16x16x32_bf16 v[38:41], v[156:159], v[180:183], v[38:41]
	v_mfma_f32_16x16x32_bf16 v[34:37], v[164:167], v[180:183], v[34:37]
	v_mfma_f32_16x16x32_bf16 v[22:25], v[156:159], v[188:191], v[22:25]
	v_mfma_f32_16x16x32_bf16 v[18:21], v[164:167], v[188:191], v[18:21]
	v_mfma_f32_16x16x32_bf16 v[6:9], v[156:159], v[222:225], v[6:9]
	v_mfma_f32_16x16x32_bf16 v[2:5], v[164:167], v[222:225], v[2:5]
	v_mfma_f32_16x16x32_bf16 v[54:57], v[160:163], v[176:179], v[54:57]
	v_mfma_f32_16x16x32_bf16 v[50:53], v[168:171], v[176:179], v[50:53]
	v_mfma_f32_16x16x32_bf16 v[38:41], v[160:163], v[184:187], v[38:41]
	v_mfma_f32_16x16x32_bf16 v[34:37], v[168:171], v[184:187], v[34:37]
	v_mfma_f32_16x16x32_bf16 v[22:25], v[160:163], v[206:209], v[22:25]
	v_mfma_f32_16x16x32_bf16 v[18:21], v[168:171], v[206:209], v[18:21]
	v_mfma_f32_16x16x32_bf16 v[6:9], v[160:163], v[226:229], v[6:9]
	v_mfma_f32_16x16x32_bf16 v[2:5], v[168:171], v[226:229], v[2:5]
	s_nop 0
	s_barrier
	s_add_i32 s56, 0, 0x18000
	s_add_i32 s57, 0, 0x1c000
	v_add_u32_e32 v152, s56, v145
	v_add_u32_e32 v168, s57, v145
	ds_read_b128 v[136:139], v152
	ds_read_b128 v[140:143], v152 offset:1024
	ds_read_b128 v[148:151], v152 offset:2048
	ds_read_b128 v[152:155], v152 offset:3072
	ds_read_b128 v[156:159], v168
	ds_read_b128 v[160:163], v168 offset:1024
	ds_read_b128 v[164:167], v168 offset:2048
	ds_read_b128 v[168:171], v168 offset:3072
	s_add_u32 s34, s34, 0x40000
	s_addc_u32 s35, s35, 0
	s_mov_b32 m0, s43
	v_lshl_add_u64 v[236:237], s[34:35], 0, v[0:1]
	ds_read_b128 v[172:175], v147 offset:32768
	ds_read_b128 v[176:179], v147 offset:33792
	ds_read_b128 v[180:183], v147 offset:34816
	ds_read_b128 v[184:187], v147 offset:35840
	ds_read_b128 v[188:191], v147 offset:36864
	ds_read_b128 v[206:209], v147 offset:37888
	ds_read_b128 v[222:225], v147 offset:38912
	ds_read_b128 v[226:229], v147 offset:39936
	global_load_lds_dwordx4 v[236:237], off
	v_lshl_add_u64 v[236:237], s[34:35], 0, v[130:131]
	s_mov_b32 m0, s44
	s_nop 0
	global_load_lds_dwordx4 v[236:237], off
	s_waitcnt vmcnt(8)
	s_waitcnt lgkmcnt(0)
	s_barrier
	s_nop 0
	s_waitcnt lgkmcnt(0)
	v_mfma_f32_16x16x32_bf16 v[126:129], v[136:139], v[172:175], v[126:129]
	v_mfma_f32_16x16x32_bf16 v[122:125], v[148:151], v[172:175], v[122:125]
	v_mfma_f32_16x16x32_bf16 v[110:113], v[136:139], v[180:183], v[110:113]
	v_mfma_f32_16x16x32_bf16 v[106:109], v[148:151], v[180:183], v[106:109]
	v_mfma_f32_16x16x32_bf16 v[94:97], v[136:139], v[188:191], v[94:97]
	v_mfma_f32_16x16x32_bf16 v[90:93], v[148:151], v[188:191], v[90:93]
	v_mfma_f32_16x16x32_bf16 v[78:81], v[136:139], v[222:225], v[78:81]
	v_mfma_f32_16x16x32_bf16 v[74:77], v[148:151], v[222:225], v[74:77]
	v_mfma_f32_16x16x32_bf16 v[126:129], v[140:143], v[176:179], v[126:129]
	v_mfma_f32_16x16x32_bf16 v[122:125], v[152:155], v[176:179], v[122:125]
	v_mfma_f32_16x16x32_bf16 v[110:113], v[140:143], v[184:187], v[110:113]
	v_mfma_f32_16x16x32_bf16 v[106:109], v[152:155], v[184:187], v[106:109]
	v_mfma_f32_16x16x32_bf16 v[94:97], v[140:143], v[206:209], v[94:97]
	v_mfma_f32_16x16x32_bf16 v[90:93], v[152:155], v[206:209], v[90:93]
	v_mfma_f32_16x16x32_bf16 v[78:81], v[140:143], v[226:229], v[78:81]
	v_mfma_f32_16x16x32_bf16 v[74:77], v[152:155], v[226:229], v[74:77]
	s_nop 0
	s_nop 0
	v_mfma_f32_16x16x32_bf16 v[118:121], v[156:159], v[172:175], v[118:121]
	v_mfma_f32_16x16x32_bf16 v[114:117], v[164:167], v[172:175], v[114:117]
	v_mfma_f32_16x16x32_bf16 v[102:105], v[156:159], v[180:183], v[102:105]
	v_mfma_f32_16x16x32_bf16 v[98:101], v[164:167], v[180:183], v[98:101]
	v_mfma_f32_16x16x32_bf16 v[86:89], v[156:159], v[188:191], v[86:89]
	v_mfma_f32_16x16x32_bf16 v[82:85], v[164:167], v[188:191], v[82:85]
	v_mfma_f32_16x16x32_bf16 v[70:73], v[156:159], v[222:225], v[70:73]
	v_mfma_f32_16x16x32_bf16 v[66:69], v[164:167], v[222:225], v[66:69]
	v_mfma_f32_16x16x32_bf16 v[118:121], v[160:163], v[176:179], v[118:121]
	v_mfma_f32_16x16x32_bf16 v[114:117], v[168:171], v[176:179], v[114:117]
	v_mfma_f32_16x16x32_bf16 v[102:105], v[160:163], v[184:187], v[102:105]
	v_mfma_f32_16x16x32_bf16 v[98:101], v[168:171], v[184:187], v[98:101]
	v_mfma_f32_16x16x32_bf16 v[86:89], v[160:163], v[206:209], v[86:89]
	v_mfma_f32_16x16x32_bf16 v[82:85], v[168:171], v[206:209], v[82:85]
	v_mfma_f32_16x16x32_bf16 v[70:73], v[160:163], v[226:229], v[70:73]
	v_mfma_f32_16x16x32_bf16 v[66:69], v[168:171], v[226:229], v[66:69]
	s_nop 0
	s_barrier
; #define PG8_STAGE(bufoff, gbase, voff) do { _Pragma("unroll") for (int _i = 0; _i < 2; ++_i) \
;         __builtin_amdgcn_global_load_lds((const unsigned*)((const char*)(gbase) + (voff)[_i]), (PG8_LAS unsigned*)(lds + (bufoff) + ldsw + _i * 8192), 16, 0, 0); } while (0)
; #define PG8_LDA(dst, b, h) do { _Pragma("unroll") for (int m = 0; m < 4; ++m) _Pragma("unroll") for (int k = 0; k < 2; ++k) dst[m][k] = *(const PG8_LAS bf16x8*)(lds + PG8_SA(b, h) + aoff + m * 2048 + k * 1024); } while (0)
; #define PG8_MMA(ai, bj, At, Bt) do { __builtin_amdgcn_s_setprio(1); _Pragma("unroll") for (int m = 0; m < 4; ++m) _Pragma("unroll") for (int n = 0; n < 2; ++n) _Pragma("unroll") for (int k = 0; k < 2; ++k) \
;         acc[ai][bj][m][n] = __builtin_amdgcn_mfma_f32_16x16x32_bf16(Bt[n][k], At[m][k], acc[ai][bj][m][n], 0, 0, 0); __builtin_amdgcn_s_setprio(0); } while (0)
; #define PG8_WAIT_V(n) asm volatile("s_waitcnt vmcnt(" #n ")" ::: "memory")
; #define PG8_WAIT_L(n) asm volatile("s_waitcnt lgkmcnt(" #n ")" ::: "memory")
; #define PG8_BAR __builtin_amdgcn_s_barrier()
; #define PG8_SCHED __builtin_amdgcn_sched_barrier(0)
; template <class Epi, class Sched, bool ALIGN_EPI = false, bool SP2 = false>
; __device__ __forceinline__ void gemm_phase(PG8_LAS unsigned char* lds, const Gemm g, const Sched& S, const Epi& E) {
;     ...
;         for (int t = 0; t < nt; t += 2) {
;             const bool last = (t == nt - 2);
;     ...
;             PG8_LDA(At, 1, 1); PG8_STAGE(PG8_SB(1, 0), b3, voffB); PG8_STAGE(PG8_SB(1, 1), b3 + hstep, voffB); PG8_STAGE(PG8_SA(1, 0), a3, voffA);
;             PG8_WAIT_V(8); PG8_WAIT_L(0); PG8_BAR; PG8_MMA(1, 0, At, B0); PG8_MMA(1, 1, At, B1); PG8_BAR; PG8_SCHED;
	s_add_i32 s34, s56, s40
	v_lshl_add_u64 v[192:193], v[192:193], 0, s[96:97]
	s_mov_b32 m0, s34
	ds_read_b128 v[172:175], v147 offset:49152
	ds_read_b128 v[176:179], v147 offset:50176
	ds_read_b128 v[180:183], v147 offset:51200
	ds_read_b128 v[184:187], v147 offset:52224
	ds_read_b128 v[188:191], v147 offset:53248
	ds_read_b128 v[206:209], v147 offset:54272
	ds_read_b128 v[222:225], v147 offset:55296
	ds_read_b128 v[226:229], v147 offset:56320
	global_load_lds_dwordx4 v[192:193], off
	s_add_i32 m0, s34, 0x2000
	s_add_u32 s6, s6, 0x40080
	v_lshl_add_u64 v[192:193], v[230:231], 0, s[96:97]
	s_addc_u32 s7, s7, 0
	s_add_i32 s34, s57, s40
	global_load_lds_dwordx4 v[192:193], off
	v_lshl_add_u64 v[192:193], s[6:7], 0, v[0:1]
	s_mov_b32 m0, s34
	s_nop 0
	global_load_lds_dwordx4 v[192:193], off
	v_lshl_add_u64 v[192:193], s[6:7], 0, v[130:131]
	s_add_i32 m0, s34, 0x2000
	s_nop 0
	global_load_lds_dwordx4 v[192:193], off
	v_lshl_add_u64 v[192:193], v[232:233], 0, s[96:97]
	s_mov_b32 m0, s47
	s_nop 0
	global_load_lds_dwordx4 v[192:193], off
	v_lshl_add_u64 v[192:193], v[234:235], 0, s[96:97]
	s_mov_b32 m0, s48
	s_nop 0
	global_load_lds_dwordx4 v[192:193], off
	s_waitcnt vmcnt(8)
	s_waitcnt lgkmcnt(0)
	s_barrier
	s_nop 0
	s_waitcnt lgkmcnt(0)
	v_mfma_f32_16x16x32_bf16 v[62:65], v[136:139], v[172:175], v[62:65]
	v_mfma_f32_16x16x32_bf16 v[58:61], v[148:151], v[172:175], v[58:61]
	v_mfma_f32_16x16x32_bf16 v[46:49], v[136:139], v[180:183], v[46:49]
	v_mfma_f32_16x16x32_bf16 v[42:45], v[148:151], v[180:183], v[42:45]
	v_mfma_f32_16x16x32_bf16 v[30:33], v[136:139], v[188:191], v[30:33]
	v_mfma_f32_16x16x32_bf16 v[26:29], v[148:151], v[188:191], v[26:29]
	v_mfma_f32_16x16x32_bf16 v[14:17], v[136:139], v[222:225], v[14:17]
	v_mfma_f32_16x16x32_bf16 v[10:13], v[148:151], v[222:225], v[10:13]
	v_mfma_f32_16x16x32_bf16 v[62:65], v[140:143], v[176:179], v[62:65]
	v_mfma_f32_16x16x32_bf16 v[58:61], v[152:155], v[176:179], v[58:61]
	v_mfma_f32_16x16x32_bf16 v[46:49], v[140:143], v[184:187], v[46:49]
	v_mfma_f32_16x16x32_bf16 v[42:45], v[152:155], v[184:187], v[42:45]
	v_mfma_f32_16x16x32_bf16 v[30:33], v[140:143], v[206:209], v[30:33]
	v_mfma_f32_16x16x32_bf16 v[26:29], v[152:155], v[206:209], v[26:29]
	v_mfma_f32_16x16x32_bf16 v[14:17], v[140:143], v[226:229], v[14:17]
	v_mfma_f32_16x16x32_bf16 v[10:13], v[152:155], v[226:229], v[10:13]
	s_nop 0
	s_nop 0
	v_mfma_f32_16x16x32_bf16 v[54:57], v[156:159], v[172:175], v[54:57]
	v_mfma_f32_16x16x32_bf16 v[50:53], v[164:167], v[172:175], v[50:53]
	v_mfma_f32_16x16x32_bf16 v[38:41], v[156:159], v[180:183], v[38:41]
	v_mfma_f32_16x16x32_bf16 v[34:37], v[164:167], v[180:183], v[34:37]
	v_mfma_f32_16x16x32_bf16 v[22:25], v[156:159], v[188:191], v[22:25]
	v_mfma_f32_16x16x32_bf16 v[18:21], v[164:167], v[188:191], v[18:21]
	v_mfma_f32_16x16x32_bf16 v[6:9], v[156:159], v[222:225], v[6:9]
	v_mfma_f32_16x16x32_bf16 v[2:5], v[164:167], v[222:225], v[2:5]
	v_mfma_f32_16x16x32_bf16 v[54:57], v[160:163], v[176:179], v[54:57]
	v_mfma_f32_16x16x32_bf16 v[50:53], v[168:171], v[176:179], v[50:53]
	v_mfma_f32_16x16x32_bf16 v[38:41], v[160:163], v[184:187], v[38:41]
	v_mfma_f32_16x16x32_bf16 v[34:37], v[168:171], v[184:187], v[34:37]
	v_mfma_f32_16x16x32_bf16 v[22:25], v[160:163], v[206:209], v[22:25]
	v_mfma_f32_16x16x32_bf16 v[18:21], v[168:171], v[206:209], v[18:21]
	v_mfma_f32_16x16x32_bf16 v[6:9], v[160:163], v[226:229], v[6:9]
	v_mfma_f32_16x16x32_bf16 v[2:5], v[168:171], v[226:229], v[2:5]
	s_nop 0
	s_barrier
	s_add_i32 s55, s55, 2
	s_add_u32 s53, s53, 0x100
	s_addc_u32 s54, s54, 0
	s_add_u32 s2, s2, 0x100
	s_addc_u32 s3, s3, 0
	s_cmp_gt_u32 s55, 13
	s_cbranch_scc0 .LBB0_601
	s_and_b64 vcc, exec, s[22:23]
	s_cbranch_vccz .LBB0_604
	s_barrier

; __device__ __forceinline__ void xbar(unsigned* ctl, unsigned k, unsigned x, unsigned nloc, unsigned nx) {
;     asm volatile("s_waitcnt vmcnt(0)" ::: "memory");
;     __syncthreads();
;     if (threadIdx.x == 0) {
;         const unsigned old = __hip_atomic_fetch_add(ctl + 2048 + 64 * x, 1u, __ATOMIC_RELAXED, __HIP_MEMORY_SCOPE_AGENT);
;         if (old + 1u == nloc * (k + 1u)) {
;             __builtin_amdgcn_fence(__ATOMIC_RELEASE, "agent");
;             __hip_atomic_fetch_add(ctl + 3072, 1u, __ATOMIC_RELAXED, __HIP_MEMORY_SCOPE_AGENT);
; __global__ void __launch_bounds__(512) hymba_fwd(Args a) {
;     ...
;         if (l == 0) SEAM(pb + 4, 6 * l + 5);
;     }
.LBB0_656:
	s_setprio 0
	v_readlane_b32 s0, v254, 33
	v_readlane_b32 s2, v253, 59
	v_readlane_b32 s1, v254, 34
	v_readlane_b32 s3, v253, 60
	s_and_b64 s[0:1], s[0:1], s[8:9]
	s_and_b64 s[2:3], s[10:11], s[2:3]
	s_and_b64 s[0:1], s[0:1], s[2:3]
	s_andn2_b64 vcc, exec, s[0:1]
	s_cbranch_vccnz .LBB0_127
	s_waitcnt vmcnt(0)
	s_waitcnt lgkmcnt(0)
	s_barrier
	s_mov_b64 s[0:1], exec
	v_readlane_b32 s2, v253, 0
	v_readlane_b32 s3, v253, 1
	s_and_b64 s[2:3], s[0:1], s[2:3]
	v_readlane_b32 s8, v253, 61
	s_mov_b64 exec, s[2:3]
	s_cbranch_execz .LBB0_126
	s_mov_b64 s[4:5], exec
	v_mbcnt_lo_u32_b32 v0, s4, 0
	v_mbcnt_hi_u32_b32 v0, s5, v0
	v_cmp_eq_u32_e32 vcc, 0, v0
	s_and_saveexec_b64 s[2:3], vcc
	s_cbranch_execz .LBB0_660
	s_bcnt1_i32_b64 s4, s[4:5]
	v_mov_b32_e32 v2, s4
	v_readlane_b32 s4, v253, 51
	v_readlane_b32 s5, v253, 52
	s_nop 4
	global_atomic_add v2, v1, v2, s[4:5] sc0
